# attention: next query block's q/k/v lines touched during the current unit (next-block prefetch); P9 rendezvous uses a returning atomic so the last arriver skips polling
# baseline (speedup 1.0000x reference)
; #define LAS __attribute__((address_space(3)))
; __device__ __forceinline__ void attn_unit(LAS unsigned char* lds, const bf16_t* Q, bf16_t* O, const bf16_t* Kb, const bf16_t* Vb, const float* sinks, int unit, int tid, int lane, int wid, int chain_ui) {
;     const int n = unit & 63, g = (unit >> 6) & 3, b = unit >> 8;
;     const int r0 = b * SEQ + n * 128;
;     const int q = lane & 31, hi = lane >> 5, hq = wid >> 1, head = 4 * g + hq;
;     bf16x8 Qf[2][4];
; #pragma unroll
;     for (int it = 0; it < 2; ++it) { const bf16_t* qp = Q + (size_t)(r0 + 32 * ((wid & 1) * 2 + it) + q) * DM + head * 64;
; #pragma unroll
;         for (int d0 = 0; d0 < 4; ++d0) Qf[it][d0] = *(const bf16x8*)(qp + 16 * d0 + 8 * hi); }
;     const bool full = chain_ui <= 0; const int par = full ? 0 : (chain_ui & 1);
;     const int ph0 = par * 128, ph1 = (par ^ 1) * 128;
;     u32x4 kk[4], vv[4];
; #pragma unroll
;     for (int i = 0; i < 4; ++i) { const int t_ = tid + 512 * (i & 1), krl = t_ >> 3, ch = t_ & 7, h = (i < 2) ? 1 : 0;
;         kk[i] = (u32x4){0u, 0u, 0u, 0u};
;         if (h == 1 || (full && n > 0)) kk[i] = *(const u32x4*)(Kb + (size_t)(r0 - 128 + h * 128 + krl) * 256 + g * 64 + ch * 8); }
; #pragma unroll
;     for (int i = 0; i < 4; ++i) { const int t_ = tid + 512 * (i & 1), kvl = t_ & 127, c = t_ >> 7, h = (i < 2) ? 1 : 0;
;         vv[i] = (u32x4){0u, 0u, 0u, 0u};
;         if (h == 1 || (full && n > 0)) vv[i] = *(const u32x4*)(Vb + (size_t)(r0 - 128 + h * 128 + kvl) * 256 + g * 64 + c * 8); }
; #pragma unroll
;     for (int i = 0; i < 4; ++i) { const int t_ = tid + 512 * (i & 1), krl = t_ >> 3, ch = t_ & 7, h = (i < 2) ? 1 : 0;
;         if (h == 1 || full) *(LAS u32x4*)(lds + KS_OFF + ((h ? ph1 : ph0) + krl) * KS_PITCH + ch * 16) = kk[i]; }
; #pragma unroll
;     for (int i = 0; i < 4; ++i) { const int t_ = tid + 512 * (i & 1), kvl = t_ & 127, c = t_ >> 7, h = (i < 2) ? 1 : 0;
;         if (h == 1 || full) { LAS bf16_t* vp = (LAS bf16_t*)(lds + VS_OFF + (c * 8) * VS_PITCH + ((h ? ph1 : ph0) + kvl) * 2);
; #pragma unroll
;             for (int e = 0; e < 8; ++e) { const unsigned w = vv[i][e >> 1]; vp[e * (VS_PITCH / 2)] = (bf16_t)((e & 1) ? (w >> 16) : (w & 0xffffu)); } } }
;     __syncthreads();
;     const int ks = (q & 0x13) | ((q & 4) << 1) | ((q & 8) >> 1);
;     const float sink = sinks[head];
; #pragma unroll
.LBB0_636:
	s_cmpk_gt_i32 s11, 0x3ff
	s_cbranch_scc1 .LBB0_653
	s_mov_b64 s[98:99], 0x40000
	s_mov_b64 s[100:101], 0x10000
	v_writelane_b32 v254, s36, 17
	s_add_u32 s25, s78, 0xc000000
	s_addc_u32 s0, s79, 0
	v_writelane_b32 v254, s37, 18
	v_writelane_b32 v254, s0, 13
	s_add_u32 s0, s78, 0x1d000000
	v_writelane_b32 v254, s0, 15
	s_addc_u32 s0, s79, 0
	v_writelane_b32 v254, s0, 19
	v_lshlrev_b32_e32 v2, 4, v78
	v_readlane_b32 s0, v254, 0
	s_lshr_b32 s0, s0, 7
	v_mov_b32_e32 v101, 0
	v_writelane_b32 v254, s0, 0
	v_and_b32_e32 v100, 0x70, v2
	v_readlane_b32 s2, v254, 7
	s_lshl_b32 s0, s2, 1
	s_and_b32 s4, s0, 2
	v_lshl_add_u64 v[2:3], s[78:79], 0, v[100:101]
	s_mov_b64 s[0:1], 0x1c000000
	v_lshl_add_u64 v[102:103], v[2:3], 0, s[0:1]
	v_add_u32_e32 v2, 0x200, v78
	v_ashrrev_i32_e32 v3, 4, v78
	v_ashrrev_i32_e32 v109, 3, v2
	v_and_b32_e32 v104, -8, v3
	v_ashrrev_i32_e32 v2, 4, v2
	s_movk_i32 s0, 0x210
	v_and_b32_e32 v106, -8, v2
	v_mul_lo_u32 v2, v104, s0
	v_add_u32_e32 v124, 0, v2
	v_mul_lo_u32 v2, v106, s0
	v_lshlrev_b32_e32 v6, 1, v79
	v_lshrrev_b32_e32 v7, 1, v78
	v_add_u32_e32 v125, 0, v2
	v_and_b32_e32 v2, 19, v78
	v_and_b32_e32 v6, 8, v6
	v_and_b32_e32 v7, 4, v7
	v_or3_b32 v127, v7, v2, v6
	v_mbcnt_lo_u32_b32 v2, -1, 0
	v_mbcnt_hi_u32_b32 v2, -1, v2
	v_and_b32_e32 v8, 64, v2
	v_xor_b32_e32 v7, 32, v2
	v_add_u32_e32 v8, 64, v8
	v_cmp_lt_i32_e32 vcc, v7, v8
	v_and_b32_e32 v1, 31, v78
	v_mad_u32_u24 v131, v1, s0, 0
	v_cndmask_b32_e32 v2, v2, v7, vcc
	v_lshlrev_b32_e32 v130, 2, v2
	v_or_b32_e32 v2, 32, v79
	v_mad_u32_u24 v132, v2, s0, 0
	s_mul_i32 s0, s2, 0x1200
	s_add_i32 s0, s0, 0
	s_add_i32 s0, s0, 0x11400
	s_movk_i32 s15, 0x90
	v_mov_b32_e32 v2, s0
	v_mad_u32_u24 v7, v1, s15, v2
	v_and_b32_e32 v2, 7, v78
	s_lshl_b32 s5, s4, 5
	v_lshl_add_u32 v9, v2, 4, s0
	s_lshl_b32 s0, s4, 6
	v_lshrrev_b32_e32 v4, 5, v79
	v_or_b32_e32 v6, 0x80, v1
	v_writelane_b32 v254, s0, 20
	s_add_i32 s0, s5, 0x60
	s_movk_i32 s1, 0x80
	s_and_b32 s0, s0, 0x60
	v_mad_i32_i24 v10, v4, -8, v6
	v_writelane_b32 v254, s0, 21
	v_cmp_gt_u32_e64 s[2:3], s1, v10
	v_mad_i32_i24 v10, v4, -8, -1
	v_add_u32_e32 v12, v10, v6
	v_writelane_b32 v254, s2, 22
	v_lshlrev_b32_e32 v98, 3, v4
	v_lshlrev_b32_e32 v128, 4, v4
	v_writelane_b32 v254, s3, 23
	v_cmp_gt_u32_e64 s[2:3], s1, v12
	v_mad_i32_i24 v12, v4, -8, -2
	v_add_u32_e32 v13, v12, v6
	v_writelane_b32 v254, s2, 24
	s_or_b32 s14, s5, 32
	v_lshrrev_b32_e32 v8, 3, v79
	v_writelane_b32 v254, s3, 25
	v_cmp_gt_u32_e64 s[2:3], s1, v13
	v_mad_i32_i24 v13, v4, -8, -3
	v_add_u32_e32 v14, v13, v6
	v_writelane_b32 v254, s2, 26
	v_ashrrev_i32_e32 v99, 3, v78
	v_add_u32_e32 v108, 0, v100
	v_writelane_b32 v254, s3, 27
	v_cmp_gt_u32_e64 s[2:3], s1, v14
	v_mad_i32_i24 v14, v4, -8, -4
	v_add_u32_e32 v15, v14, v6
	v_writelane_b32 v254, s2, 28
	v_mul_lo_u32 v3, v99, s15
	v_mul_lo_u32 v5, v109, s15
	v_writelane_b32 v254, s3, 29
	v_cmp_gt_u32_e64 s[2:3], s1, v15
	v_mad_i32_i24 v15, v4, -8, -5
	v_add_u32_e32 v16, v15, v6
	v_writelane_b32 v254, s2, 30
	v_and_b32_e32 v123, 0x7f, v78
	v_lshlrev_b32_e32 v2, 3, v2
	v_writelane_b32 v254, s3, 31
	v_cmp_gt_u32_e64 s[2:3], s1, v16
	v_mad_i32_i24 v16, v4, -8, -6
	v_add_u32_e32 v17, v16, v6
	v_writelane_b32 v254, s2, 32
	v_mul_u32_u24_e32 v11, 0x90, v8
	v_or_b32_e32 v122, 0xffffff80, v78
	v_writelane_b32 v254, s3, 33
	v_cmp_gt_u32_e64 s[2:3], s1, v17
	v_mad_i32_i24 v17, v4, -8, -7
	v_add_u32_e32 v18, v17, v6
	v_writelane_b32 v254, s2, 34
	v_ashrrev_i32_e32 v105, 31, v104
	v_ashrrev_i32_e32 v107, 31, v106
	v_writelane_b32 v254, s3, 35
	v_cmp_gt_u32_e64 s[2:3], s1, v18
	v_mad_i32_i24 v18, v4, -8, -16
	v_add_u32_e32 v19, v18, v6
	v_writelane_b32 v254, s2, 36
	s_mov_b32 s9, 0
	v_lshlrev_b32_e32 v126, 1, v123
	v_writelane_b32 v254, s3, 37
	v_cmp_gt_u32_e64 s[2:3], s1, v19
	v_not_b32_e32 v19, 16
	v_mad_i32_i24 v19, v4, -8, v19
	v_writelane_b32 v254, s2, 38
	v_add_u32_e32 v20, v19, v6
	v_add_u32_e32 v129, 0, v128
	v_writelane_b32 v254, s3, 39
	v_cmp_gt_u32_e64 s[2:3], s1, v20
	v_not_b32_e32 v20, 17
	v_mad_i32_i24 v20, v4, -8, v20
	v_writelane_b32 v254, s2, 40
	v_add_u32_e32 v21, v20, v6
	v_add_u32_e32 v133, v108, v3
	v_writelane_b32 v254, s3, 41
	v_cmp_gt_u32_e64 s[2:3], s1, v21
	v_not_b32_e32 v21, 18
	v_mad_i32_i24 v21, v4, -8, v21
	v_writelane_b32 v254, s2, 42
	v_add_u32_e32 v22, v21, v6
	v_add_u32_e32 v134, v108, v5
	v_writelane_b32 v254, s3, 43
	v_cmp_gt_u32_e64 s[2:3], s1, v22
	v_not_b32_e32 v22, 19
	v_mad_i32_i24 v22, v4, -8, v22
	v_add_u32_e32 v23, v22, v6
	v_cmp_gt_u32_e64 s[26:27], s1, v23
	v_not_b32_e32 v23, 20
	v_mad_i32_i24 v23, v4, -8, v23
	v_add_u32_e32 v24, v23, v6
	v_cmp_gt_u32_e64 s[28:29], s1, v24
	v_not_b32_e32 v24, 21
	v_mad_i32_i24 v24, v4, -8, v24
	v_add_u32_e32 v25, v24, v6
	v_cmp_gt_u32_e64 s[30:31], s1, v25
	v_not_b32_e32 v25, 22
	v_mad_i32_i24 v25, v4, -8, v25
	v_mad_i32_i24 v4, v4, -8, v1
	v_cmp_lt_i32_e64 s[36:37], -1, v4
	v_add_u32_e32 v4, v10, v1
	v_cmp_lt_i32_e64 s[38:39], -1, v4
	v_add_u32_e32 v4, v12, v1
	v_cmp_lt_i32_e64 s[40:41], -1, v4
	v_add_u32_e32 v4, v13, v1
	v_cmp_lt_i32_e64 s[42:43], -1, v4
	v_add_u32_e32 v4, v14, v1
	v_cmp_lt_i32_e64 s[44:45], -1, v4
	v_add_u32_e32 v4, v15, v1
	v_cmp_lt_i32_e64 s[46:47], -1, v4
	v_add_u32_e32 v4, v16, v1
	v_cmp_lt_i32_e64 s[48:49], -1, v4
	v_add_u32_e32 v4, v17, v1
	v_cmp_lt_i32_e64 s[50:51], -1, v4
	v_add_u32_e32 v4, v18, v1
	v_cmp_lt_i32_e64 s[52:53], -1, v4
	v_add_u32_e32 v4, v19, v1
	v_cmp_lt_i32_e64 s[54:55], -1, v4
	v_add_u32_e32 v4, v20, v1
	v_cmp_lt_i32_e64 s[56:57], -1, v4
	v_add_u32_e32 v4, v21, v1
	v_cmp_lt_i32_e64 s[58:59], -1, v4
	v_add_u32_e32 v4, v22, v1
	v_cmp_lt_i32_e64 s[60:61], -1, v4
	v_add_u32_e32 v4, v23, v1
	v_cmp_lt_i32_e64 s[62:63], -1, v4
	v_add_u32_e32 v4, v24, v1
	v_add_u32_e32 v6, v25, v6
	v_cmp_lt_i32_e64 s[64:65], -1, v4
	v_add_u32_e32 v4, v25, v1
	v_cmp_gt_u32_e64 s[34:35], s1, v6
	v_cmp_lt_i32_e64 s[66:67], -1, v4
	v_lshlrev_b32_e32 v4, 10, v8
	v_or_b32_e32 v6, 8, v8
	s_and_b64 s[0:1], exec, s[6:7]
	v_mul_u32_u24_e32 v12, 0x90, v6
	v_lshlrev_b32_e32 v6, 10, v6
	v_or_b32_e32 v8, 0x4000, v4
	v_or_b32_e32 v10, 0x6000, v4
	s_cselect_b32 s16, s33, 1
	v_writelane_b32 v254, s2, 44
	s_lshl_b32 s17, s11, 5
	s_lshl_b32 s18, s16, 5
	v_lshlrev_b32_e32 v110, 1, v2
	s_mov_b32 s19, 0xff61b1e6
	v_add_u32_e32 v135, v7, v98
	v_add_u32_e32 v136, v9, v11
	v_lshlrev_b32_e32 v112, 1, v4
	v_add_u32_e32 v137, v9, v12
	v_lshlrev_b32_e32 v114, 1, v6
	v_lshlrev_b32_e32 v116, 1, v8
	v_lshlrev_b32_e32 v118, 1, v10
	v_mov_b32_e32 v138, 0xf149f2ca
	s_mov_b32 s20, 0
	s_mov_b32 s10, 0x3fb8aa3b
	v_writelane_b32 v254, s3, 45
	s_branch .LBB0_639
; #define LAS __attribute__((address_space(3)))
; __device__ __forceinline__ void attn_unit(LAS unsigned char* lds, const bf16_t* Q, bf16_t* O, const bf16_t* Kb, const bf16_t* Vb, const float* sinks, int unit, int tid, int lane, int wid, int chain_ui) {
;     ...
;     for (int it = 0; it < 2; ++it) {
;         const int rb = (wid & 1) * 2 + it;
;         f32x16 S[5];
; #pragma unroll
;         for (int j = 0; j < 5; ++j) {
; #pragma unroll
;             for (int r = 0; r < 16; ++r) S[j][r] = 0.f;
; #pragma unroll
;             for (int d0 = 0; d0 < 4; ++d0) { const bf16x8 Kf = *(const LAS bf16x8*)(lds + KS_OFF + ((((rb + j) >> 2) ? ph1 : ph0) + ((32 * (rb + j)) & 127) + ks) * KS_PITCH + (16 * d0 + 8 * hi) * 2);
;                 S[j] = __builtin_amdgcn_mfma_f32_32x32x16_bf16(Kf, Qf[it][d0], S[j], 0, 0, 0); } }
;         float mx = -3.0e38f;
; #pragma unroll
;         for (int j = 0; j < 5; ++j) { const bool tile_ok = (n > 0) || (rb + j >= 4);
; #pragma unroll
;             for (int r = 0; r < 16; ++r) { const int off = 16 * (r >> 3) + 8 * hi + (r & 7), diff = 128 + q - 32 * j - off;
;                 bool ok = tile_ok; if (j == 0) ok = ok && (diff < 128); if (j == 4) ok = ok && (diff >= 0);
;                 const float sv = ok ? S[j][r] * 0.125f : -1e30f; S[j][r] = sv; mx = fmaxf(mx, sv); } }
.LBB0_638:
	s_or_b32 vcc_lo, s72, s5
	v_or_b32_e32 v2, vcc_lo, v127
	v_mad_u32_u24 v22, v2, s15, v129
	s_waitcnt lgkmcnt(0)
	s_barrier
	ds_read_b128 v[2:5], v22
	ds_read_b128 v[18:21], v22 offset:32
	s_waitcnt lgkmcnt(1)
	v_mfma_f32_32x32x16_bf16 v[2:17], v[2:5], v[62:65], 0
	s_lshl_b32 s2, s23, 2
	s_or_b32 s23, s72, s14
	v_readlane_b32 s3, v254, 20
	s_xor_b32 s3, s72, s3
	v_mov_b32_e32 v141, s2
	s_or_b32 s2, s3, s5
	v_readlane_b32 s24, v254, 21
	s_waitcnt lgkmcnt(0)
	v_mfma_f32_32x32x16_bf16 v[2:17], v[18:21], v[58:61], v[2:17]
	ds_read_b128 v[18:21], v22 offset:64
	ds_read_b128 v[22:25], v22 offset:96
	v_mov_b32_e32 v111, v101
	s_or_b32 vcc_hi, s3, s24
	v_bitop3_b32 v30, s2, v127, 64 bitop3:0xde
	v_lshl_add_u64 v[120:121], s[68:69], 0, v[110:111]
	v_or_b32_e32 v31, vcc_hi, v127
	s_waitcnt lgkmcnt(1)
	v_mfma_f32_32x32x16_bf16 v[2:17], v[18:21], v[54:57], v[2:17]
	v_or_b32_e32 v18, s23, v127
	v_mad_u32_u24 v139, v18, s15, v129
	ds_read_b128 v[18:21], v139
	v_mad_u32_u24 v111, v30, s15, v129
	v_mad_u32_u24 v100, v31, s15, v129
	v_readlane_b32 s68, v254, 28
	v_readlane_b32 s69, v254, 29
	s_waitcnt lgkmcnt(0)
	v_mfma_f32_32x32x16_bf16 v[32:47], v[18:21], v[62:65], 0
	s_and_b64 s[96:97], s[0:1], s[68:69]
	v_readlane_b32 s68, v254, 30
	v_readlane_b32 s69, v254, 31
	s_and_b64 s[94:95], s[0:1], s[68:69]
	v_readlane_b32 s68, v254, 32
	v_readlane_b32 s69, v254, 33
	s_and_b64 s[92:93], s[0:1], s[68:69]
	v_mfma_f32_32x32x16_bf16 v[2:17], v[22:25], v[50:53], v[2:17]
	ds_read_b128 v[22:25], v139 offset:32
	ds_read_b128 v[26:29], v139 offset:64
	ds_read_b128 v[66:69], v139 offset:96
	ds_read_b128 v[18:21], v111
	ds_read_b128 v[70:73], v111 offset:32
	ds_read_b128 v[158:161], v111 offset:64
	ds_read_b128 v[162:165], v111 offset:96
	ds_read_b128 v[166:169], v100
	ds_read_b128 v[170:173], v100 offset:32
	v_readlane_b32 s68, v254, 34
	v_readlane_b32 s69, v254, 35
	s_and_b64 s[90:91], s[0:1], s[68:69]
	v_readlane_b32 s68, v254, 36
	v_readlane_b32 s69, v254, 37
	s_waitcnt lgkmcnt(8)
	v_mfma_f32_32x32x16_bf16 v[32:47], v[22:25], v[58:61], v[32:47]
	v_mul_f32_e32 v48, 0x3e000000, v2
	v_mul_f32_e32 v49, 0x3e000000, v3
	v_mul_f32_e32 v155, 0x3e000000, v4
	v_mul_f32_e32 v156, 0x3e000000, v5
	v_mul_f32_e32 v154, 0x3e000000, v6
	v_mul_f32_e32 v153, 0x3e000000, v7
	v_mul_f32_e32 v151, 0x3e000000, v8
	s_waitcnt lgkmcnt(7)
	v_mfma_f32_32x32x16_bf16 v[32:47], v[26:29], v[54:57], v[32:47]
	v_mul_f32_e32 v152, 0x3e000000, v9
	v_mul_f32_e32 v149, 0x3e000000, v10
	v_mul_f32_e32 v150, 0x3e000000, v11
	v_mul_f32_e32 v148, 0x3e000000, v12
	v_mul_f32_e32 v146, 0x3e000000, v13
	v_mul_f32_e32 v145, 0x3e000000, v14
	v_mul_f32_e32 v147, 0x3e000000, v15
	s_waitcnt lgkmcnt(6)
	v_mfma_f32_32x32x16_bf16 v[32:47], v[66:69], v[50:53], v[32:47]
	v_mul_f32_e32 v143, 0x3e000000, v16
	v_mul_f32_e32 v144, 0x3e000000, v17
	s_and_b64 s[88:89], s[0:1], s[68:69]
	v_readlane_b32 s68, v254, 38
	v_readlane_b32 s69, v254, 39
	s_xor_b32 s24, s2, 64
	v_readlane_b32 s2, v254, 22
	s_nop 4
	v_mul_f32_e32 v2, 0x3e000000, v32
	v_cndmask_b32_e64 v119, v138, v2, s[0:1]
	v_mul_f32_e32 v2, 0x3e000000, v33
	v_cndmask_b32_e64 v142, v138, v2, s[0:1]
	v_mul_f32_e32 v2, 0x3e000000, v34
	s_waitcnt lgkmcnt(5)
	v_mfma_f32_32x32x16_bf16 v[18:33], v[18:21], v[62:65], 0
	v_cndmask_b32_e64 v81, v138, v2, s[0:1]
	v_mul_f32_e32 v2, 0x3e000000, v35
	v_cndmask_b32_e64 v113, v138, v2, s[0:1]
	v_mul_f32_e32 v2, 0x3e000000, v36
	v_cndmask_b32_e64 v115, v138, v2, s[0:1]
	v_mul_f32_e32 v2, 0x3e000000, v37
	v_cndmask_b32_e64 v117, v138, v2, s[0:1]
	v_mul_f32_e32 v2, 0x3e000000, v38
	v_cndmask_b32_e64 v77, v138, v2, s[0:1]
	v_mul_f32_e32 v2, 0x3e000000, v39
	v_cndmask_b32_e64 v78, v138, v2, s[0:1]
	v_mul_f32_e32 v2, 0x3e000000, v40
	v_cndmask_b32_e64 v79, v138, v2, s[0:1]
	v_mul_f32_e32 v2, 0x3e000000, v41
	v_cndmask_b32_e64 v80, v138, v2, s[0:1]
	v_mul_f32_e32 v2, 0x3e000000, v42
	s_waitcnt lgkmcnt(4)
	v_mfma_f32_32x32x16_bf16 v[18:33], v[70:73], v[58:61], v[18:33]
	v_cndmask_b32_e64 v73, v138, v2, s[0:1]
	v_mul_f32_e32 v2, 0x3e000000, v43
	v_cndmask_b32_e64 v74, v138, v2, s[0:1]
	v_mul_f32_e32 v2, 0x3e000000, v44
	v_cndmask_b32_e64 v75, v138, v2, s[0:1]
	v_mul_f32_e32 v2, 0x3e000000, v45
	v_cndmask_b32_e64 v76, v138, v2, s[0:1]
	v_mul_f32_e32 v2, 0x3e000000, v46
	v_cndmask_b32_e64 v71, v138, v2, s[0:1]
	v_mul_f32_e32 v2, 0x3e000000, v47
	v_cndmask_b32_e64 v72, v138, v2, s[0:1]
	s_waitcnt lgkmcnt(1)
	v_mfma_f32_32x32x16_bf16 v[2:17], v[166:169], v[62:65], 0
	s_and_b64 s[86:87], s[0:1], s[68:69]
	v_readlane_b32 s68, v254, 40
	v_readlane_b32 s3, v254, 23
	v_readlane_b32 s69, v254, 41
	s_and_b64 s[72:73], s[0:1], s[2:3]
	v_readlane_b32 s2, v254, 24
	s_and_b64 s[84:85], s[0:1], s[68:69]
	s_waitcnt lgkmcnt(0)
	v_mfma_f32_32x32x16_bf16 v[2:17], v[170:173], v[58:61], v[2:17]
	v_readlane_b32 s68, v254, 42
	v_readlane_b32 s3, v254, 25
	v_readlane_b32 s69, v254, 43
	ds_read_b128 v[34:37], v100 offset:64
	ds_read_b128 v[38:41], v100 offset:96
	s_and_b64 s[74:75], s[0:1], s[2:3]
	v_readlane_b32 s2, v254, 26
	s_and_b64 s[82:83], s[0:1], s[68:69]
	v_readlane_b32 s68, v254, 44
	v_readlane_b32 s3, v254, 27
	v_readlane_b32 s69, v254, 45
	s_and_b64 s[2:3], s[0:1], s[2:3]
	s_and_b64 s[80:81], s[0:1], s[68:69]
	s_and_b64 s[78:79], s[0:1], s[26:27]
	s_and_b64 s[76:77], s[0:1], s[28:29]
	s_and_b64 s[70:71], s[0:1], s[30:31]
	s_and_b64 s[68:69], s[0:1], s[34:35]
	s_or_b32 s0, s22, s4
	s_or_b32 s1, s8, s5
	s_cmp_eq_u32 s0, 0
	s_waitcnt lgkmcnt(1)
	v_mfma_f32_32x32x16_bf16 v[2:17], v[34:37], v[54:57], v[2:17]
	v_or_b32_e32 v34, s1, v127
	v_lshl_or_b32 v66, s1, 1, v128
	v_readlane_b32 s0, v254, 1
	v_readlane_b32 s1, v254, 2
	s_load_dwordx2 s[0:1], s[0:1], 0x60
	v_mad_u32_u24 v140, v34, s15, v129
	ds_read_b128 v[34:37], v140
	v_mfma_f32_32x32x16_bf16 v[18:33], v[158:161], v[54:57], v[18:33]
	v_cndmask_b32_e64 v157, v138, v48, s[72:73]
	s_waitcnt lgkmcnt(0)
; __device__ __forceinline__ void attn_unit(LAS unsigned char* lds, const bf16_t* Q, bf16_t* O, const bf16_t* Kb, const bf16_t* Vb, const float* sinks, int unit, int tid, int lane, int wid, int chain_ui) {
;     ...
;         float mx = -3.0e38f;
; #pragma unroll
;         for (int j = 0; j < 5; ++j) { const bool tile_ok = (n > 0) || (rb + j >= 4);
; #pragma unroll
;             for (int r = 0; r < 16; ++r) { const int off = 16 * (r >> 3) + 8 * hi + (r & 7), diff = 128 + q - 32 * j - off;
;                 bool ok = tile_ok; if (j == 0) ok = ok && (diff < 128); if (j == 4) ok = ok && (diff >= 0);
;                 const float sv = ok ? S[j][r] * 0.125f : -1e30f; S[j][r] = sv; mx = fmaxf(mx, sv); } }
;         mx = fmaxf(mx, __shfl_xor(mx, 32)); mx = fmaxf(mx, sink);
	global_load_dword v141, v141, s[0:1]
	v_cndmask_b32_e64 v170, v138, v49, s[74:75]
	v_cndmask_b32_e64 v153, v138, v153, s[92:93]
	v_cndmask_b32_e64 v148, v138, v148, s[82:83]
	s_cselect_b64 s[0:1], -1, 0
	v_lshl_or_b32 v70, vcc_lo, 1, v128
	v_mfma_f32_32x32x16_bf16 v[2:17], v[38:41], v[50:53], v[2:17]
	v_lshl_or_b32 v69, s23, 1, v128
	v_lshl_or_b32 v68, s24, 1, v128
	v_lshl_or_b32 v67, vcc_hi, 1, v128
	v_mfma_f32_32x32x16_bf16 v[34:49], v[34:37], v[62:65], 0
	v_max3_f32 v62, v157, s19, v170
	v_cndmask_b32_e64 v63, v138, v155, s[2:3]
	v_cndmask_b32_e64 v64, v138, v156, s[96:97]
	v_max3_f32 v62, v62, v63, v64
	v_cndmask_b32_e64 v65, v138, v154, s[94:95]
	v_max3_f32 v62, v62, v65, v153
	s_nop 1
	v_mul_f32_e32 v2, 0x3e000000, v2
	v_mfma_f32_32x32x16_bf16 v[18:33], v[162:165], v[50:53], v[18:33]
	ds_read_b128 v[158:161], v140 offset:32
	ds_read_b128 v[162:165], v140 offset:64
	ds_read_b128 v[166:169], v140 offset:96
	v_mul_f32_e32 v3, 0x3e000000, v3
	v_cndmask_b32_e64 v2, v2, v138, s[0:1]
	v_cndmask_b32_e64 v3, v3, v138, s[0:1]
	v_mul_f32_e32 v4, 0x3e000000, v4
	v_mul_f32_e32 v5, 0x3e000000, v5
	v_cndmask_b32_e64 v4, v4, v138, s[0:1]
	s_waitcnt lgkmcnt(2)
	v_mfma_f32_32x32x16_bf16 v[34:49], v[158:161], v[58:61], v[34:49]
	v_cndmask_b32_e64 v58, v138, v151, s[90:91]
	v_cndmask_b32_e64 v59, v138, v152, s[88:89]
	v_max3_f32 v60, v62, v58, v59
	v_cndmask_b32_e64 v61, v138, v149, s[86:87]
	v_cndmask_b32_e64 v62, v138, v150, s[84:85]
	v_max3_f32 v60, v60, v61, v62
	v_mul_f32_e32 v18, 0x3e000000, v18
	s_waitcnt lgkmcnt(1)
	v_mfma_f32_32x32x16_bf16 v[34:49], v[162:165], v[54:57], v[34:49]
	v_cndmask_b32_e64 v54, v138, v146, s[80:81]
	v_max3_f32 v55, v60, v148, v54
	v_cndmask_b32_e64 v56, v138, v145, s[78:79]
	v_cndmask_b32_e64 v57, v138, v147, s[76:77]
	v_max3_f32 v55, v55, v56, v57
	v_cndmask_b32_e64 v60, v138, v143, s[70:71]
	v_cndmask_b32_e64 v143, v138, v144, s[68:69]
	s_waitcnt lgkmcnt(0)
	v_mfma_f32_32x32x16_bf16 v[34:49], v[166:169], v[50:53], v[34:49]
	v_max3_f32 v50, v55, v60, v143
	v_max3_f32 v50, v50, v119, v142
	v_max3_f32 v50, v50, v81, v113
	v_max3_f32 v50, v50, v115, v117
	v_max3_f32 v50, v50, v77, v78
	v_max3_f32 v50, v50, v79, v80
	v_max3_f32 v50, v50, v73, v74
	v_max3_f32 v50, v50, v75, v76
	v_mul_f32_e32 v19, 0x3e000000, v19
	v_max3_f32 v50, v50, v71, v72
	v_cndmask_b32_e64 v18, v18, v138, s[0:1]
	v_cndmask_b32_e64 v19, v19, v138, s[0:1]
	v_mul_f32_e32 v20, 0x3e000000, v20
	v_mul_f32_e32 v21, 0x3e000000, v21
	v_max3_f32 v50, v50, v18, v19
	v_cndmask_b32_e64 v20, v20, v138, s[0:1]
	v_cndmask_b32_e64 v21, v21, v138, s[0:1]
	v_mul_f32_e32 v22, 0x3e000000, v22
	v_mul_f32_e32 v23, 0x3e000000, v23
	v_max3_f32 v50, v50, v20, v21
	v_cndmask_b32_e64 v22, v22, v138, s[0:1]
	v_cndmask_b32_e64 v23, v23, v138, s[0:1]
	v_mul_f32_e32 v24, 0x3e000000, v24
	v_mul_f32_e32 v25, 0x3e000000, v25
	v_max3_f32 v50, v50, v22, v23
	v_cndmask_b32_e64 v24, v24, v138, s[0:1]
	v_cndmask_b32_e64 v25, v25, v138, s[0:1]
	v_mul_f32_e32 v26, 0x3e000000, v26
	v_mul_f32_e32 v27, 0x3e000000, v27
	v_max3_f32 v50, v50, v24, v25
	v_cndmask_b32_e64 v26, v26, v138, s[0:1]
	v_cndmask_b32_e64 v27, v27, v138, s[0:1]
	v_mul_f32_e32 v28, 0x3e000000, v28
	v_mul_f32_e32 v29, 0x3e000000, v29
	v_max3_f32 v50, v50, v26, v27
	v_cndmask_b32_e64 v28, v28, v138, s[0:1]
	v_cndmask_b32_e64 v29, v29, v138, s[0:1]
	v_mul_f32_e32 v30, 0x3e000000, v30
	v_mul_f32_e32 v31, 0x3e000000, v31
	v_max3_f32 v50, v50, v28, v29
	v_cndmask_b32_e64 v30, v30, v138, s[0:1]
	v_cndmask_b32_e64 v31, v31, v138, s[0:1]
	v_mul_f32_e32 v32, 0x3e000000, v32
	v_mul_f32_e32 v33, 0x3e000000, v33
	v_max3_f32 v50, v50, v30, v31
	v_cndmask_b32_e64 v32, v32, v138, s[0:1]
	v_cndmask_b32_e64 v33, v33, v138, s[0:1]
	v_max3_f32 v50, v50, v32, v33
	v_max3_f32 v50, v50, v2, v3
	v_cndmask_b32_e64 v5, v5, v138, s[0:1]
	v_mul_f32_e32 v6, 0x3e000000, v6
	v_mul_f32_e32 v7, 0x3e000000, v7
	v_max3_f32 v50, v50, v4, v5
	v_cndmask_b32_e64 v6, v6, v138, s[0:1]
	v_cndmask_b32_e64 v7, v7, v138, s[0:1]
	v_mul_f32_e32 v8, 0x3e000000, v8
	v_mul_f32_e32 v9, 0x3e000000, v9
	v_max3_f32 v50, v50, v6, v7
	v_cndmask_b32_e64 v8, v8, v138, s[0:1]
	v_cndmask_b32_e64 v9, v9, v138, s[0:1]
	v_mul_f32_e32 v10, 0x3e000000, v10
	v_mul_f32_e32 v11, 0x3e000000, v11
	v_max3_f32 v50, v50, v8, v9
	v_cndmask_b32_e64 v10, v10, v138, s[0:1]
	v_cndmask_b32_e64 v11, v11, v138, s[0:1]
	v_mul_f32_e32 v12, 0x3e000000, v12
	v_mul_f32_e32 v13, 0x3e000000, v13
	v_max3_f32 v50, v50, v10, v11
	v_cndmask_b32_e64 v12, v12, v138, s[0:1]
	v_cndmask_b32_e64 v13, v13, v138, s[0:1]
	v_mul_f32_e32 v14, 0x3e000000, v14
	v_mul_f32_e32 v15, 0x3e000000, v15
	v_mul_f32_e32 v16, 0x3e000000, v16
	v_max3_f32 v50, v50, v12, v13
	v_cndmask_b32_e64 v14, v14, v138, s[0:1]
	v_cndmask_b32_e64 v15, v15, v138, s[0:1]
	v_cndmask_b32_e64 v51, v16, v138, s[0:1]
	v_mul_f32_e32 v16, 0x3e000000, v17
	v_max3_f32 v50, v50, v14, v15
	v_cndmask_b32_e64 v52, v16, v138, s[0:1]
	v_mul_f32_e32 v17, 0x3e000000, v34
	v_max3_f32 v16, v50, v51, v52
	v_cndmask_b32_e64 v50, v138, v17, s[36:37]
	v_mul_f32_e32 v17, 0x3e000000, v35
	v_cndmask_b32_e64 v55, v138, v17, s[38:39]
	v_mul_f32_e32 v17, 0x3e000000, v36
	v_cndmask_b32_e64 v144, v138, v17, s[40:41]
	v_mul_f32_e32 v17, 0x3e000000, v37
	v_cndmask_b32_e64 v145, v138, v17, s[42:43]
	v_mul_f32_e32 v17, 0x3e000000, v38
	v_cndmask_b32_e64 v146, v138, v17, s[44:45]
	v_mul_f32_e32 v17, 0x3e000000, v39
	v_cndmask_b32_e64 v147, v138, v17, s[46:47]
	v_mul_f32_e32 v17, 0x3e000000, v40
	v_cndmask_b32_e64 v149, v138, v17, s[48:49]
	v_mul_f32_e32 v17, 0x3e000000, v41
	v_cndmask_b32_e64 v150, v138, v17, s[50:51]
	v_mul_f32_e32 v17, 0x3e000000, v42
	v_cndmask_b32_e64 v151, v138, v17, s[52:53]
	v_mul_f32_e32 v17, 0x3e000000, v43
	v_max3_f32 v16, v16, v50, v55
	v_cndmask_b32_e64 v152, v138, v17, s[54:55]
	v_mul_f32_e32 v17, 0x3e000000, v44
	v_max3_f32 v16, v16, v144, v145
	v_cndmask_b32_e64 v154, v138, v17, s[56:57]
	v_mul_f32_e32 v17, 0x3e000000, v45
	v_max3_f32 v16, v16, v146, v147
	v_cndmask_b32_e64 v155, v138, v17, s[58:59]
	v_mul_f32_e32 v17, 0x3e000000, v46
	v_max3_f32 v16, v16, v149, v150
	v_cndmask_b32_e64 v156, v138, v17, s[60:61]
	v_mul_f32_e32 v17, 0x3e000000, v47
	v_max3_f32 v16, v16, v151, v152
	v_cndmask_b32_e64 v158, v138, v17, s[62:63]
	v_mul_f32_e32 v17, 0x3e000000, v48
	v_max3_f32 v16, v16, v154, v155
	v_cndmask_b32_e64 v159, v138, v17, s[64:65]
	v_mul_f32_e32 v17, 0x3e000000, v49
	v_max3_f32 v16, v16, v156, v158
	v_cndmask_b32_e64 v34, v138, v17, s[66:67]
	v_max3_f32 v16, v16, v159, v34
	ds_bpermute_b32 v17, v130, v16
	s_waitcnt vmcnt(0) lgkmcnt(0)
; __device__ __forceinline__ unsigned cvt_pk_bf16(float lo, float hi) { unsigned r; asm volatile("v_cvt_pk_bf16_f32 %0, %1, %2" : "=v"(r) : "v"(lo), "v"(hi)); return r; }
; #define LAS __attribute__((address_space(3)))
; __device__ __forceinline__ void attn_unit(LAS unsigned char* lds, const bf16_t* Q, bf16_t* O, const bf16_t* Kb, const bf16_t* Vb, const float* sinks, int unit, int tid, int lane, int wid, int chain_ui) {
;     ...
;         mx = fmaxf(mx, __shfl_xor(mx, 32)); mx = fmaxf(mx, sink);
;         const float L2E = 1.4426950408889634f, mneg = -mx * L2E;
;         float sum = 0.f;
; #pragma unroll
;         for (int j = 0; j < 5; ++j)
; #pragma unroll
;             for (int r = 0; r < 16; ++r) { const float pv = __builtin_amdgcn_exp2f(S[j][r] * L2E + mneg); S[j][r] = pv; sum += pv; }
;         sum += __shfl_xor(sum, 32);
;         const float inv = 1.0f / (sum + __builtin_amdgcn_exp2f((sink - mx) * L2E));
;         f32x16 O0, O1;
; #pragma unroll
;         for (int r = 0; r < 16; ++r) { O0[r] = 0.f; O1[r] = 0.f; }
; #pragma unroll
;         for (int j = 0; j < 5; ++j)
; #pragma unroll
;             for (int st = 0; st < 2; ++st) {
;                 u32x4 pw; pw.x = pg8::cvt_pk_bf16(S[j][8 * st + 0], S[j][8 * st + 1]); pw.y = pg8::cvt_pk_bf16(S[j][8 * st + 2], S[j][8 * st + 3]);
;                 pw.z = pg8::cvt_pk_bf16(S[j][8 * st + 4], S[j][8 * st + 5]); pw.w = pg8::cvt_pk_bf16(S[j][8 * st + 6], S[j][8 * st + 7]);
;                 const bf16x8 Pf = __builtin_bit_cast(bf16x8, pw);
;                 const int kvoff = ((((rb + j) >> 2) ? ph1 : ph0) + ((32 * (rb + j)) & 127) + 16 * st + 8 * hi) * 2;
;                 const bf16x8 V0 = *(const LAS bf16x8*)(lds + VS_OFF + q * VS_PITCH + kvoff), V1 = *(const LAS bf16x8*)(lds + VS_OFF + (32 + q) * VS_PITCH + kvoff);
;                 O0 = __builtin_amdgcn_mfma_f32_32x32x16_bf16(V0, Pf, O0, 0, 0, 0); O1 = __builtin_amdgcn_mfma_f32_32x32x16_bf16(V1, Pf, O1, 0, 0, 0); }
	global_load_dword v192, v[180:181], off
	global_load_dword v192, v[180:181], off offset:64
	global_load_dword v192, v[182:183], off
	global_load_dword v192, v[182:183], off offset:64
	global_load_dword v192, v[184:185], off
	global_load_dword v192, v[186:187], off
	global_load_dword v192, v[188:189], off
	global_load_dword v192, v[190:191], off
	v_max3_f32 v35, v16, v17, v141
	v_pk_mul_f32 v[36:37], v[34:35], s[10:11] op_sel_hi:[1,0]
	s_nop 0
	v_fma_f32 v16, v157, s10, -v37
	v_exp_f32_e32 v16, v16
	v_fma_f32 v17, v170, s10, -v37
	v_exp_f32_e32 v17, v17
	v_fma_f32 v38, v63, s10, -v37
	v_exp_f32_e32 v38, v38
	v_fma_f32 v39, v64, s10, -v37
	v_exp_f32_e32 v39, v39
	v_fma_f32 v40, v65, s10, -v37
	v_add_f32_e32 v34, 0, v16
	v_exp_f32_e32 v40, v40
	v_fma_f32 v41, v153, s10, -v37
	v_add_f32_e32 v34, v17, v34
	v_exp_f32_e32 v41, v41
	v_fma_f32 v42, v58, s10, -v37
	v_add_f32_e32 v34, v38, v34
	v_exp_f32_e32 v42, v42
	v_fma_f32 v43, v59, s10, -v37
	v_add_f32_e32 v34, v39, v34
	v_exp_f32_e32 v43, v43
	v_fma_f32 v44, v61, s10, -v37
	v_add_f32_e32 v34, v40, v34
	v_exp_f32_e32 v44, v44
	v_fma_f32 v45, v62, s10, -v37
	v_add_f32_e32 v34, v41, v34
	v_exp_f32_e32 v45, v45
	v_fma_f32 v46, v148, s10, -v37
	v_add_f32_e32 v34, v42, v34
	v_exp_f32_e32 v46, v46
	v_fma_f32 v47, v54, s10, -v37
	v_add_f32_e32 v34, v43, v34
	v_exp_f32_e32 v47, v47
	v_fma_f32 v48, v56, s10, -v37
	v_add_f32_e32 v34, v44, v34
	v_exp_f32_e32 v48, v48
	v_fma_f32 v49, v57, s10, -v37
	v_add_f32_e32 v34, v45, v34
	v_exp_f32_e32 v49, v49
	v_fma_f32 v53, v60, s10, -v37
	v_add_f32_e32 v34, v46, v34
	v_exp_f32_e32 v53, v53
	v_fma_f32 v54, v143, s10, -v37
	v_add_f32_e32 v34, v47, v34
	v_exp_f32_e32 v54, v54
	v_fma_f32 v56, v119, s10, -v37
	v_add_f32_e32 v34, v48, v34
	v_exp_f32_e32 v56, v56
	v_fma_f32 v57, v142, s10, -v37
	v_add_f32_e32 v34, v49, v34
	v_exp_f32_e32 v57, v57
	v_fma_f32 v58, v81, s10, -v37
	v_add_f32_e32 v34, v53, v34
	v_exp_f32_e32 v58, v58
	v_fma_f32 v59, v113, s10, -v37
	v_add_f32_e32 v34, v54, v34
	v_exp_f32_e32 v59, v59
	v_fma_f32 v60, v115, s10, -v37
	v_add_f32_e32 v34, v56, v34
	v_exp_f32_e32 v60, v60
	v_fma_f32 v61, v117, s10, -v37
	v_add_f32_e32 v34, v57, v34
	v_exp_f32_e32 v61, v61
	v_fma_f32 v62, v77, s10, -v37
	v_add_f32_e32 v34, v58, v34
	v_exp_f32_e32 v62, v62
	v_fma_f32 v63, v78, s10, -v37
	v_add_f32_e32 v34, v59, v34
	v_exp_f32_e32 v63, v63
	v_fma_f32 v64, v79, s10, -v37
	v_add_f32_e32 v34, v60, v34
	v_exp_f32_e32 v64, v64
	v_fma_f32 v65, v80, s10, -v37
	v_add_f32_e32 v34, v61, v34
	v_exp_f32_e32 v65, v65
	v_fma_f32 v73, v73, s10, -v37
	v_add_f32_e32 v34, v62, v34
	v_exp_f32_e32 v73, v73
	v_fma_f32 v74, v74, s10, -v37
	v_add_f32_e32 v34, v63, v34
	v_exp_f32_e32 v74, v74
	v_fma_f32 v75, v75, s10, -v37
	v_add_f32_e32 v34, v64, v34
	v_exp_f32_e32 v75, v75
	v_fma_f32 v76, v76, s10, -v37
	v_add_f32_e32 v34, v65, v34
	v_exp_f32_e32 v76, v76
	v_fma_f32 v71, v71, s10, -v37
	v_add_f32_e32 v34, v73, v34
	v_exp_f32_e32 v71, v71
	v_fma_f32 v72, v72, s10, -v37
	v_add_f32_e32 v34, v74, v34
	v_exp_f32_e32 v72, v72
	v_fma_f32 v18, v18, s10, -v37
	v_add_f32_e32 v34, v75, v34
	v_exp_f32_e32 v77, v18
	v_fma_f32 v18, v19, s10, -v37
	v_add_f32_e32 v34, v76, v34
	v_exp_f32_e32 v78, v18
	v_fma_f32 v19, v20, s10, -v37
	v_add_f32_e32 v18, v71, v34
	v_exp_f32_e32 v34, v19
	v_fma_f32 v19, v21, s10, -v37
	v_add_f32_e32 v18, v72, v18
	v_exp_f32_e32 v79, v19
	v_fma_f32 v19, v22, s10, -v37
	v_add_f32_e32 v18, v77, v18
	v_exp_f32_e32 v80, v19
	v_fma_f32 v19, v23, s10, -v37
	v_add_f32_e32 v18, v78, v18
	v_exp_f32_e32 v81, v19
	v_fma_f32 v19, v24, s10, -v37
	v_add_f32_e32 v18, v34, v18
	v_exp_f32_e32 v113, v19
	v_fma_f32 v19, v25, s10, -v37
	v_add_f32_e32 v18, v79, v18
	v_exp_f32_e32 v115, v19
	v_fma_f32 v19, v26, s10, -v37
	v_add_f32_e32 v18, v80, v18
	v_exp_f32_e32 v117, v19
	v_fma_f32 v19, v27, s10, -v37
	v_add_f32_e32 v18, v81, v18
	v_exp_f32_e32 v119, v19
	v_fma_f32 v19, v28, s10, -v37
	v_add_f32_e32 v18, v113, v18
	v_exp_f32_e32 v148, v19
	v_fma_f32 v19, v29, s10, -v37
	v_add_f32_e32 v18, v115, v18
	v_exp_f32_e32 v153, v19
	v_fma_f32 v19, v30, s10, -v37
	v_add_f32_e32 v18, v117, v18
	v_exp_f32_e32 v157, v19
	v_fma_f32 v19, v31, s10, -v37
	v_add_f32_e32 v18, v119, v18
	v_exp_f32_e32 v160, v19
	v_fma_f32 v19, v32, s10, -v37
	v_add_f32_e32 v18, v148, v18
	v_exp_f32_e32 v161, v19
	v_fma_f32 v19, v33, s10, -v37
	v_add_f32_e32 v18, v153, v18
	v_exp_f32_e32 v162, v19
	v_fma_f32 v2, v2, s10, -v37
	v_add_f32_e32 v18, v157, v18
	v_exp_f32_e32 v163, v2
	v_fma_f32 v2, v3, s10, -v37
	v_add_f32_e32 v18, v160, v18
	v_exp_f32_e32 v164, v2
	v_fma_f32 v3, v4, s10, -v37
	v_add_f32_e32 v2, v161, v18
	v_exp_f32_e32 v165, v3
	v_fma_f32 v3, v5, s10, -v37
	v_add_f32_e32 v2, v162, v2
	v_exp_f32_e32 v166, v3
	v_fma_f32 v3, v6, s10, -v37
	v_add_f32_e32 v2, v163, v2
	v_exp_f32_e32 v167, v3
	v_fma_f32 v3, v7, s10, -v37
	v_add_f32_e32 v2, v164, v2
	v_exp_f32_e32 v168, v3
	v_fma_f32 v3, v8, s10, -v37
	v_add_f32_e32 v2, v165, v2
	v_exp_f32_e32 v169, v3
	v_fma_f32 v3, v9, s10, -v37
	v_add_f32_e32 v2, v166, v2
	v_exp_f32_e32 v170, v3
	v_fma_f32 v3, v10, s10, -v37
	v_add_f32_e32 v2, v167, v2
	v_exp_f32_e32 v171, v3
	v_fma_f32 v3, v11, s10, -v37
	v_add_f32_e32 v2, v168, v2
	v_exp_f32_e32 v172, v3
	v_add_f32_e32 v2, v169, v2
	v_add_f32_e32 v2, v170, v2
	v_add_f32_e32 v2, v171, v2
	v_add_f32_e32 v6, v172, v2
	v_fma_f32 v2, v12, s10, -v37
	v_exp_f32_e32 v173, v2
	v_fma_f32 v2, v13, s10, -v37
	v_exp_f32_e32 v174, v2
	v_fma_f32 v2, v14, s10, -v37
	v_add_u32_e32 v26, v131, v70
	v_add_u32_e32 v70, v132, v70
	v_exp_f32_e32 v175, v2
	v_cvt_pk_bf16_f32 v18, v16, v17
	v_cvt_pk_bf16_f32 v19, v38, v39
	v_cvt_pk_bf16_f32 v20, v40, v41
	v_cvt_pk_bf16_f32 v21, v42, v43
	ds_read_b128 v[2:5], v26 offset:36864
	ds_read_b128 v[22:25], v70 offset:36864
	v_fma_f32 v7, v15, s10, -v37
	v_exp_f32_e32 v176, v7
	v_fma_f32 v27, v51, s10, -v37
	v_add_f32_e32 v6, v173, v6
	v_exp_f32_e32 v177, v27
	v_cvt_pk_bf16_f32 v38, v44, v45
	v_cvt_pk_bf16_f32 v39, v46, v47
	v_fma_f32 v46, v52, s10, -v37
	v_add_f32_e32 v6, v174, v6
	v_cvt_pk_bf16_f32 v40, v48, v49
	v_cvt_pk_bf16_f32 v41, v53, v54
	v_exp_f32_e32 v54, v46
	v_add_f32_e32 v6, v175, v6
	v_add_f32_e32 v142, v176, v6
	v_add_f32_e32 v46, v177, v142
	v_fma_f32 v47, v50, s10, -v37
	ds_read_b128 v[42:45], v26 offset:36896
	v_exp_f32_e32 v178, v47
	v_add_f32_e32 v50, v54, v46
	ds_read_b128 v[46:49], v70 offset:36896
	s_waitcnt lgkmcnt(3)
; __device__ __forceinline__ unsigned cvt_pk_bf16(float lo, float hi) { unsigned r; asm volatile("v_cvt_pk_bf16_f32 %0, %1, %2" : "=v"(r) : "v"(lo), "v"(hi)); return r; }
; #define LAS __attribute__((address_space(3)))
; __device__ __forceinline__ void attn_unit(LAS unsigned char* lds, const bf16_t* Q, bf16_t* O, const bf16_t* Kb, const bf16_t* Vb, const float* sinks, int unit, int tid, int lane, int wid, int chain_ui) {
;     ...
;             for (int r = 0; r < 16; ++r) { const float pv = __builtin_amdgcn_exp2f(S[j][r] * L2E + mneg); S[j][r] = pv; sum += pv; }
;         sum += __shfl_xor(sum, 32);
;         const float inv = 1.0f / (sum + __builtin_amdgcn_exp2f((sink - mx) * L2E));
;         f32x16 O0, O1;
; #pragma unroll
;         for (int r = 0; r < 16; ++r) { O0[r] = 0.f; O1[r] = 0.f; }
; #pragma unroll
;         for (int j = 0; j < 5; ++j)
; #pragma unroll
;             for (int st = 0; st < 2; ++st) {
;                 u32x4 pw; pw.x = pg8::cvt_pk_bf16(S[j][8 * st + 0], S[j][8 * st + 1]); pw.y = pg8::cvt_pk_bf16(S[j][8 * st + 2], S[j][8 * st + 3]);
;                 pw.z = pg8::cvt_pk_bf16(S[j][8 * st + 4], S[j][8 * st + 5]); pw.w = pg8::cvt_pk_bf16(S[j][8 * st + 6], S[j][8 * st + 7]);
;                 const bf16x8 Pf = __builtin_bit_cast(bf16x8, pw);
;                 const int kvoff = ((((rb + j) >> 2) ? ph1 : ph0) + ((32 * (rb + j)) & 127) + 16 * st + 8 * hi) * 2;
;                 const bf16x8 V0 = *(const LAS bf16x8*)(lds + VS_OFF + q * VS_PITCH + kvoff), V1 = *(const LAS bf16x8*)(lds + VS_OFF + (32 + q) * VS_PITCH + kvoff);
;                 O0 = __builtin_amdgcn_mfma_f32_32x32x16_bf16(V0, Pf, O0, 0, 0, 0); O1 = __builtin_amdgcn_mfma_f32_32x32x16_bf16(V1, Pf, O1, 0, 0, 0); }
	v_mfma_f32_32x32x16_bf16 v[2:17], v[2:5], v[18:21], 0
	v_add_u32_e32 v142, v131, v69
	v_add_f32_e32 v70, v178, v50
	v_add_u32_e32 v143, v131, v68
	s_waitcnt lgkmcnt(2)
	v_mfma_f32_32x32x16_bf16 v[18:33], v[22:25], v[18:21], 0
	s_waitcnt lgkmcnt(1)
	v_mfma_f32_32x32x16_bf16 v[2:17], v[42:45], v[38:41], v[2:17]
	v_cvt_pk_bf16_f32 v42, v56, v57
	v_cvt_pk_bf16_f32 v43, v58, v59
	v_cvt_pk_bf16_f32 v44, v60, v61
	v_cvt_pk_bf16_f32 v45, v62, v63
	ds_read_b128 v[50:53], v142 offset:36864
	v_fma_f32 v58, v146, s10, -v37
	v_exp_f32_e32 v58, v58
	s_waitcnt lgkmcnt(1)
	v_mfma_f32_32x32x16_bf16 v[18:33], v[46:49], v[38:41], v[18:33]
	v_fma_f32 v38, v55, s10, -v37
	v_exp_f32_e32 v55, v38
	v_fma_f32 v38, v144, s10, -v37
	v_add_u32_e32 v144, v132, v69
	v_exp_f32_e32 v56, v38
	ds_read_b128 v[38:41], v144 offset:36864
	v_fma_f32 v46, v145, s10, -v37
	v_exp_f32_e32 v57, v46
	s_waitcnt lgkmcnt(0)
	v_mfma_f32_32x32x16_bf16 v[18:33], v[38:41], v[42:45], v[18:33]
	v_add_f32_e32 v38, v55, v70
	v_add_f32_e32 v38, v56, v38
	v_add_f32_e32 v38, v57, v38
	v_cvt_pk_bf16_f32 v46, v64, v65
	v_cvt_pk_bf16_f32 v47, v73, v74
	v_cvt_pk_bf16_f32 v48, v75, v76
	v_cvt_pk_bf16_f32 v49, v71, v72
	v_mfma_f32_32x32x16_bf16 v[2:17], v[50:53], v[42:45], v[2:17]
	ds_read_b128 v[50:53], v142 offset:36896
	v_add_f32_e32 v59, v58, v38
	ds_read_b128 v[38:41], v144 offset:36896
	v_fma_f32 v42, v147, s10, -v37
	v_exp_f32_e32 v60, v42
	v_cvt_pk_bf16_f32 v42, v77, v78
	v_cvt_pk_bf16_f32 v43, v34, v79
	s_waitcnt lgkmcnt(0)
	v_mfma_f32_32x32x16_bf16 v[18:33], v[38:41], v[46:49], v[18:33]
	v_fma_f32 v38, v149, s10, -v37
	v_add_f32_e32 v34, v60, v59
	v_exp_f32_e32 v59, v38
	v_fma_f32 v38, v150, s10, -v37
	v_add_u32_e32 v146, v132, v68
	v_cvt_pk_bf16_f32 v44, v80, v81
	v_cvt_pk_bf16_f32 v45, v113, v115
	v_mfma_f32_32x32x16_bf16 v[2:17], v[50:53], v[46:49], v[2:17]
	ds_read_b128 v[50:53], v143 offset:36864
	v_exp_f32_e32 v61, v38
	ds_read_b128 v[38:41], v146 offset:36864
	v_cvt_pk_bf16_f32 v46, v117, v119
	v_cvt_pk_bf16_f32 v47, v148, v153
	v_cvt_pk_bf16_f32 v48, v157, v160
	v_cvt_pk_bf16_f32 v49, v161, v162
	s_waitcnt lgkmcnt(0)
	v_mfma_f32_32x32x16_bf16 v[18:33], v[38:41], v[42:45], v[18:33]
	v_fma_f32 v38, v151, s10, -v37
	v_exp_f32_e32 v62, v38
	v_fma_f32 v38, v152, s10, -v37
	v_exp_f32_e32 v63, v38
	v_fma_f32 v38, v154, s10, -v37
	v_exp_f32_e32 v64, v38
	ds_read_b128 v[38:41], v146 offset:36896
	v_mfma_f32_32x32x16_bf16 v[2:17], v[50:53], v[42:45], v[2:17]
	ds_read_b128 v[50:53], v143 offset:36896
	v_add_u32_e32 v145, v131, v67
	v_cvt_pk_bf16_f32 v42, v163, v164
	v_cvt_pk_bf16_f32 v43, v165, v166
	v_cvt_pk_bf16_f32 v44, v167, v168
	v_cvt_pk_bf16_f32 v45, v169, v170
	v_add_u32_e32 v148, v132, v67
	s_waitcnt lgkmcnt(0)
	v_mfma_f32_32x32x16_bf16 v[2:17], v[50:53], v[46:49], v[2:17]
	ds_read_b128 v[50:53], v145 offset:36864
	v_add_f32_e32 v34, v59, v34
	v_fma_f32 v65, v155, s10, -v37
	v_add_f32_e32 v34, v61, v34
	v_exp_f32_e32 v65, v65
	v_add_f32_e32 v34, v62, v34
	v_add_f32_e32 v34, v63, v34
	v_mfma_f32_32x32x16_bf16 v[18:33], v[38:41], v[46:49], v[18:33]
	ds_read_b128 v[38:41], v148 offset:36864
	v_fma_f32 v46, v156, s10, -v37
	v_exp_f32_e32 v67, v46
	v_cvt_pk_bf16_f32 v46, v171, v172
	v_cvt_pk_bf16_f32 v47, v173, v174
	v_cvt_pk_bf16_f32 v48, v175, v176
	v_cvt_pk_bf16_f32 v49, v177, v54
	s_waitcnt lgkmcnt(1)
	v_mfma_f32_32x32x16_bf16 v[2:17], v[50:53], v[42:45], v[2:17]
	ds_read_b128 v[50:53], v145 offset:36896
	v_add_f32_e32 v34, v64, v34
	v_add_f32_e32 v34, v65, v34
	v_add_u32_e32 v147, v131, v66
	v_add_f32_e32 v34, v67, v34
	v_add_u32_e32 v149, v132, v66
	v_mov_b32_e32 v113, v101
	s_waitcnt lgkmcnt(1)
	v_mfma_f32_32x32x16_bf16 v[18:33], v[38:41], v[42:45], v[18:33]
	v_fma_f32 v38, v158, s10, -v37
	v_exp_f32_e32 v54, v38
	v_fma_f32 v38, v159, s10, -v37
	v_exp_f32_e32 v68, v38
	v_sub_f32_e32 v40, v36, v37
	ds_read_b128 v[36:39], v148 offset:36896
	v_exp_f32_e32 v69, v40
	s_waitcnt lgkmcnt(1)
	v_mfma_f32_32x32x16_bf16 v[2:17], v[50:53], v[46:49], v[2:17]
	v_cvt_pk_bf16_f32 v40, v178, v55
	v_cvt_pk_bf16_f32 v41, v56, v57
	v_cvt_pk_bf16_f32 v42, v58, v60
	v_cvt_pk_bf16_f32 v43, v59, v61
	ds_read_b128 v[50:53], v147 offset:36864
	v_add_f32_e32 v34, v54, v34
	v_add_f32_e32 v34, v68, v34
	s_waitcnt lgkmcnt(1)
	v_mfma_f32_32x32x16_bf16 v[18:33], v[36:39], v[46:49], v[18:33]
	v_add_f32_e32 v38, v69, v34
	v_sub_f32_e32 v44, v141, v35
	ds_read_b128 v[34:37], v149 offset:36864
	ds_bpermute_b32 v39, v130, v38
	v_mul_f32_e32 v44, 0x3fb8aa3b, v44
	v_mov_b32_e32 v115, v101
	v_mov_b32_e32 v117, v101
	s_waitcnt lgkmcnt(2)
	v_mfma_f32_32x32x16_bf16 v[2:17], v[50:53], v[40:43], v[2:17]
	v_exp_f32_e32 v52, v44
	v_cvt_pk_bf16_f32 v44, v62, v63
	v_cvt_pk_bf16_f32 v45, v64, v65
	v_cvt_pk_bf16_f32 v46, v67, v54
	v_cvt_pk_bf16_f32 v47, v68, v69
	ds_read_b128 v[48:51], v147 offset:36896
	v_mov_b32_e32 v119, v101
	s_waitcnt lgkmcnt(2)
	v_mfma_f32_32x32x16_bf16 v[18:33], v[34:37], v[40:43], v[18:33]
	s_waitcnt lgkmcnt(1)
	v_add_f32_e32 v34, v38, v39
	v_add_f32_e32 v40, v52, v34
	ds_read_b128 v[34:37], v149 offset:36896
	v_div_scale_f32 v38, s[22:23], v40, v40, 1.0
	v_rcp_f32_e32 v39, v38
	s_or_b32 s22, s21, s5
	s_waitcnt lgkmcnt(1)
	v_mfma_f32_32x32x16_bf16 v[2:17], v[48:51], v[44:47], v[2:17]
	s_ashr_i32 s23, s22, 31
	v_fma_f32 v41, -v38, v39, 1.0
	v_fmac_f32_e32 v39, v41, v39
	v_div_scale_f32 v41, vcc, 1.0, v40, 1.0
	v_mul_f32_e32 v42, v41, v39
	v_fma_f32 v43, -v38, v42, v41
	s_waitcnt lgkmcnt(0)
; #define LAS __attribute__((address_space(3)))
; __device__ __forceinline__ void attn_unit(LAS unsigned char* lds, const bf16_t* Q, bf16_t* O, const bf16_t* Kb, const bf16_t* Vb, const float* sinks, int unit, int tid, int lane, int wid, int chain_ui) {
;     ...
;     for (int it = 0; it < 2; ++it) {
;         const int rb = (wid & 1) * 2 + it;
;         f32x16 S[5];
; #pragma unroll
;         for (int j = 0; j < 5; ++j) {
; #pragma unroll
;             for (int r = 0; r < 16; ++r) S[j][r] = 0.f;
; #pragma unroll
;             for (int d0 = 0; d0 < 4; ++d0) { const bf16x8 Kf = *(const LAS bf16x8*)(lds + KS_OFF + ((((rb + j) >> 2) ? ph1 : ph0) + ((32 * (rb + j)) & 127) + ks) * KS_PITCH + (16 * d0 + 8 * hi) * 2);
;                 S[j] = __builtin_amdgcn_mfma_f32_32x32x16_bf16(Kf, Qf[it][d0], S[j], 0, 0, 0); } }
;         float mx = -3.0e38f;
; #pragma unroll
;         for (int j = 0; j < 5; ++j) { const bool tile_ok = (n > 0) || (rb + j >= 4);
; #pragma unroll
;             for (int r = 0; r < 16; ++r) { const int off = 16 * (r >> 3) + 8 * hi + (r & 7), diff = 128 + q - 32 * j - off;
;                 bool ok = tile_ok; if (j == 0) ok = ok && (diff < 128); if (j == 4) ok = ok && (diff >= 0);
;                 const float sv = ok ? S[j][r] * 0.125f : -1e30f; S[j][r] = sv; mx = fmaxf(mx, sv); } }
;     ...
;         { LAS unsigned char* ost = lds + OS_OFF + wid * OS_WAVE;
; #pragma unroll
;           for (int r4 = 0; r4 < 4; ++r4) { const int d = 8 * r4 + 4 * hi;
;             u32x2 w0, w1; w0.x = pg8::cvt_pk_bf16(O0[4 * r4] * inv, O0[4 * r4 + 1] * inv); w0.y = pg8::cvt_pk_bf16(O0[4 * r4 + 2] * inv, O0[4 * r4 + 3] * inv);
;             w1.x = pg8::cvt_pk_bf16(O1[4 * r4] * inv, O1[4 * r4 + 1] * inv); w1.y = pg8::cvt_pk_bf16(O1[4 * r4 + 2] * inv, O1[4 * r4 + 3] * inv);
;             *(LAS u32x2*)(ost + q * OS_PITCH + d * 2) = w0; *(LAS u32x2*)(ost + q * OS_PITCH + (32 + d) * 2) = w1; }
;           __builtin_amdgcn_wave_barrier(); asm volatile("" ::: "memory");
;           bf16_t* ob = O + (size_t)(r0 + 32 * rb) * DM + head * 64;
; #pragma unroll
;           for (int ps = 0; ps < 4; ++ps) { const int rr = 8 * ps + (lane >> 3), pc = lane & 7;
;             const u32x4 v = *(const LAS u32x4*)(ost + rr * OS_PITCH + pc * 16);
;             *(u32x4*)(ob + (size_t)rr * DM + pc * 8) = v; }
	v_mfma_f32_32x32x16_bf16 v[18:33], v[34:37], v[44:47], v[18:33]
	v_fmac_f32_e32 v42, v43, v39
	v_fma_f32 v38, -v38, v42, v41
	v_div_fmas_f32 v41, v38, v39, v42
	v_div_fixup_f32 v34, v41, v40, 1.0
	v_mul_f32_e32 v2, v2, v34
	v_mul_f32_e32 v3, v3, v34
	v_cvt_pk_bf16_f32 v2, v2, v3
	v_mul_f32_e32 v3, v4, v34
	v_mul_f32_e32 v4, v5, v34
	v_cvt_pk_bf16_f32 v3, v3, v4
	s_nop 3
	v_mul_f32_e32 v4, v18, v34
	v_mul_f32_e32 v5, v19, v34
	v_cvt_pk_bf16_f32 v4, v4, v5
	v_mul_f32_e32 v5, v20, v34
	v_mul_f32_e32 v18, v21, v34
	v_cvt_pk_bf16_f32 v5, v5, v18
	ds_write2_b64 v135, v[2:3], v[4:5] offset1:8
	v_mul_f32_e32 v2, v6, v34
	v_mul_f32_e32 v3, v7, v34
	v_cvt_pk_bf16_f32 v2, v2, v3
	v_mul_f32_e32 v3, v8, v34
	v_mul_f32_e32 v4, v9, v34
	v_cvt_pk_bf16_f32 v3, v3, v4
	v_mul_f32_e32 v4, v22, v34
	v_mul_f32_e32 v5, v23, v34
	v_cvt_pk_bf16_f32 v4, v4, v5
	v_mul_f32_e32 v5, v24, v34
	v_mul_f32_e32 v6, v25, v34
	v_cvt_pk_bf16_f32 v5, v5, v6
	ds_write2_b64 v135, v[2:3], v[4:5] offset0:2 offset1:10
	v_mul_f32_e32 v2, v10, v34
	v_mul_f32_e32 v3, v11, v34
	v_cvt_pk_bf16_f32 v2, v2, v3
	v_mul_f32_e32 v3, v12, v34
	v_mul_f32_e32 v4, v13, v34
	v_cvt_pk_bf16_f32 v3, v3, v4
	v_mul_f32_e32 v4, v26, v34
	v_mul_f32_e32 v5, v27, v34
	v_cvt_pk_bf16_f32 v4, v4, v5
	v_mul_f32_e32 v5, v28, v34
	v_mul_f32_e32 v6, v29, v34
	v_cvt_pk_bf16_f32 v5, v5, v6
	ds_write2_b64 v135, v[2:3], v[4:5] offset0:4 offset1:12
	v_mul_f32_e32 v2, v14, v34
	v_mul_f32_e32 v3, v15, v34
	v_cvt_pk_bf16_f32 v2, v2, v3
	v_mul_f32_e32 v3, v16, v34
	v_mul_f32_e32 v4, v17, v34
	v_cvt_pk_bf16_f32 v3, v3, v4
	v_mul_f32_e32 v4, v30, v34
	v_mul_f32_e32 v5, v31, v34
	v_cvt_pk_bf16_f32 v4, v4, v5
	v_mul_f32_e32 v5, v32, v34
	v_mul_f32_e32 v6, v33, v34
	v_cvt_pk_bf16_f32 v5, v5, v6
	ds_write2_b64 v135, v[2:3], v[4:5] offset0:6 offset1:14
	ds_read_b128 v[2:5], v136
	ds_read_b128 v[6:9], v137
	s_lshl_b64 s[22:23], s[22:23], 11
	v_lshl_add_u64 v[38:39], v[120:121], 0, s[22:23]
	v_lshl_add_u64 v[10:11], v[38:39], 0, v[112:113]
	s_waitcnt lgkmcnt(1)
	global_store_dwordx4 v[10:11], v[2:5], off
	v_lshl_add_u64 v[10:11], v[38:39], 0, v[114:115]
	ds_read_b128 v[2:5], v137 offset:1152
	s_waitcnt lgkmcnt(1)
	global_store_dwordx4 v[10:11], v[6:9], off
	ds_read_b128 v[6:9], v137 offset:2304
	v_lshl_add_u64 v[10:11], v[38:39], 0, v[116:117]
	s_waitcnt lgkmcnt(1)
	global_store_dwordx4 v[10:11], v[2:5], off
	s_nop 1
	v_lshl_add_u64 v[2:3], v[38:39], 0, v[118:119]
	s_waitcnt lgkmcnt(0)
	global_store_dwordx4 v[2:3], v[6:9], off
	ds_read_b128 v[2:5], v139
	ds_read_b128 v[6:9], v139 offset:32
	s_waitcnt lgkmcnt(1)
	v_mfma_f32_32x32x16_bf16 v[66:81], v[2:5], v[94:97], 0
	s_waitcnt lgkmcnt(0)
	v_mfma_f32_32x32x16_bf16 v[66:81], v[6:9], v[90:93], v[66:81]
	ds_read_b128 v[2:5], v139 offset:64
	ds_read_b128 v[6:9], v139 offset:96
	s_waitcnt lgkmcnt(1)
	v_mfma_f32_32x32x16_bf16 v[66:81], v[2:5], v[86:89], v[66:81]
	s_waitcnt lgkmcnt(0)
	v_mfma_f32_32x32x16_bf16 v[66:81], v[6:9], v[82:85], v[66:81]
	ds_read_b128 v[2:5], v111
	ds_read_b128 v[6:9], v111 offset:32
	s_waitcnt lgkmcnt(1)
	v_mfma_f32_32x32x16_bf16 v[50:65], v[2:5], v[94:97], 0
	s_nop 7
	v_mul_f32_e32 v70, 0x3e000000, v70
	s_waitcnt lgkmcnt(0)
	v_mfma_f32_32x32x16_bf16 v[50:65], v[6:9], v[90:93], v[50:65]
	ds_read_b128 v[2:5], v111 offset:64
	ds_read_b128 v[6:9], v111 offset:96
	s_waitcnt lgkmcnt(1)
	v_mfma_f32_32x32x16_bf16 v[50:65], v[2:5], v[86:89], v[50:65]
	s_waitcnt lgkmcnt(0)
	v_mfma_f32_32x32x16_bf16 v[50:65], v[6:9], v[82:85], v[50:65]
	ds_read_b128 v[2:5], v100
	ds_read_b128 v[6:9], v100 offset:32
	s_waitcnt lgkmcnt(1)
	v_mfma_f32_32x32x16_bf16 v[18:33], v[2:5], v[94:97], 0
	s_nop 7
	v_mul_f32_e32 v50, 0x3e000000, v50
	s_waitcnt lgkmcnt(0)
	v_mfma_f32_32x32x16_bf16 v[18:33], v[6:9], v[90:93], v[18:33]
	ds_read_b128 v[2:5], v100 offset:64
	ds_read_b128 v[6:9], v100 offset:96
	s_waitcnt lgkmcnt(1)
	v_mfma_f32_32x32x16_bf16 v[18:33], v[2:5], v[86:89], v[18:33]
	ds_read_b128 v[2:5], v140
	ds_read_b128 v[34:37], v140 offset:32
	s_waitcnt lgkmcnt(2)
	v_mfma_f32_32x32x16_bf16 v[18:33], v[6:9], v[82:85], v[18:33]
	s_waitcnt lgkmcnt(1)
	v_mfma_f32_32x32x16_bf16 v[2:17], v[2:5], v[94:97], 0
	s_nop 9
	v_mul_f32_e32 v18, 0x3e000000, v18
	v_mul_f32_e32 v19, 0x3e000000, v19
	v_cndmask_b32_e64 v18, v18, v138, s[0:1]
	v_cndmask_b32_e64 v19, v19, v138, s[0:1]
	v_mul_f32_e32 v20, 0x3e000000, v20
	v_mul_f32_e32 v21, 0x3e000000, v21
	v_cndmask_b32_e64 v20, v20, v138, s[0:1]
	s_waitcnt lgkmcnt(0)
	v_mfma_f32_32x32x16_bf16 v[2:17], v[34:37], v[90:93], v[2:17]
	ds_read_b128 v[34:37], v140 offset:64
	ds_read_b128 v[38:41], v140 offset:96
	v_cndmask_b32_e64 v21, v21, v138, s[0:1]
	v_mul_f32_e32 v22, 0x3e000000, v22
	v_mul_f32_e32 v23, 0x3e000000, v23
	v_cndmask_b32_e64 v22, v22, v138, s[0:1]
	v_cndmask_b32_e64 v23, v23, v138, s[0:1]
	v_mul_f32_e32 v24, 0x3e000000, v24
	s_waitcnt lgkmcnt(1)
	v_mfma_f32_32x32x16_bf16 v[2:17], v[34:37], v[86:89], v[2:17]
	v_mul_f32_e32 v34, 0x3e000000, v66
	v_cndmask_b32_e64 v100, v138, v34, s[72:73]
	v_mul_f32_e32 v34, 0x3e000000, v67
	v_cndmask_b32_e64 v111, v138, v34, s[74:75]
	v_mul_f32_e32 v34, 0x3e000000, v68
	v_cndmask_b32_e64 v139, v138, v34, s[2:3]
	v_mul_f32_e32 v34, 0x3e000000, v69
	s_or_b32 s2, s8, s14
	v_cndmask_b32_e64 v140, v138, v34, s[96:97]
	v_or_b32_e32 v34, s2, v127
	v_mad_u32_u24 v150, v34, s15, v129
	ds_read_b128 v[34:37], v150
	ds_read_b128 v[66:69], v150 offset:32
	s_waitcnt lgkmcnt(2)
	v_mfma_f32_32x32x16_bf16 v[2:17], v[38:41], v[82:85], v[2:17]
	v_mul_f32_e32 v25, 0x3e000000, v25
	v_cndmask_b32_e64 v24, v24, v138, s[0:1]
	v_cndmask_b32_e64 v25, v25, v138, s[0:1]
	v_mul_f32_e32 v26, 0x3e000000, v26
	v_mul_f32_e32 v27, 0x3e000000, v27
	v_cndmask_b32_e64 v26, v26, v138, s[0:1]
	v_cndmask_b32_e64 v27, v27, v138, s[0:1]
	s_waitcnt lgkmcnt(1)
; __device__ __forceinline__ void attn_unit(LAS unsigned char* lds, const bf16_t* Q, bf16_t* O, const bf16_t* Kb, const bf16_t* Vb, const float* sinks, int unit, int tid, int lane, int wid, int chain_ui) {
;     ...
;         float mx = -3.0e38f;
; #pragma unroll
;         for (int j = 0; j < 5; ++j) { const bool tile_ok = (n > 0) || (rb + j >= 4);
; #pragma unroll
;             for (int r = 0; r < 16; ++r) { const int off = 16 * (r >> 3) + 8 * hi + (r & 7), diff = 128 + q - 32 * j - off;
;                 bool ok = tile_ok; if (j == 0) ok = ok && (diff < 128); if (j == 4) ok = ok && (diff >= 0);
;                 const float sv = ok ? S[j][r] * 0.125f : -1e30f; S[j][r] = sv; mx = fmaxf(mx, sv); } }
;         mx = fmaxf(mx, __shfl_xor(mx, 32)); mx = fmaxf(mx, sink);
	v_mfma_f32_32x32x16_bf16 v[34:49], v[34:37], v[94:97], 0
	v_cndmask_b32_e64 v94, v138, v70, s[94:95]
	v_mul_f32_e32 v70, 0x3e000000, v71
	v_cndmask_b32_e64 v95, v138, v70, s[92:93]
	v_mul_f32_e32 v70, 0x3e000000, v72
	v_cndmask_b32_e64 v96, v138, v70, s[90:91]
	v_mul_f32_e32 v70, 0x3e000000, v73
	v_cndmask_b32_e64 v97, v138, v70, s[88:89]
	s_waitcnt lgkmcnt(0)
	v_mfma_f32_32x32x16_bf16 v[34:49], v[66:69], v[90:93], v[34:49]
	ds_read_b128 v[66:69], v150 offset:64
	ds_read_b128 v[70:73], v150 offset:96
	v_mul_f32_e32 v28, 0x3e000000, v28
	v_mul_f32_e32 v29, 0x3e000000, v29
	v_cndmask_b32_e64 v28, v28, v138, s[0:1]
	v_cndmask_b32_e64 v29, v29, v138, s[0:1]
	v_mul_f32_e32 v30, 0x3e000000, v30
	v_mul_f32_e32 v31, 0x3e000000, v31
	s_waitcnt lgkmcnt(1)
	v_mfma_f32_32x32x16_bf16 v[34:49], v[66:69], v[86:89], v[34:49]
	v_mul_f32_e32 v67, 0x3e000000, v75
	v_cndmask_b32_e64 v75, v50, v138, s[0:1]
	v_mul_f32_e32 v50, 0x3e000000, v51
	v_mul_f32_e32 v51, 0x3e000000, v52
	v_cndmask_b32_e64 v52, v51, v138, s[0:1]
	v_mul_f32_e32 v51, 0x3e000000, v53
	v_mul_f32_e32 v66, 0x3e000000, v74
	s_waitcnt lgkmcnt(0)
	v_mfma_f32_32x32x16_bf16 v[34:49], v[70:73], v[82:85], v[34:49]
	v_max3_f32 v70, v100, s19, v111
	v_max3_f32 v70, v70, v139, v140
	v_max3_f32 v70, v70, v94, v95
	v_cndmask_b32_e64 v53, v51, v138, s[0:1]
	v_mul_f32_e32 v51, 0x3e000000, v54
	v_cndmask_b32_e64 v66, v138, v66, s[86:87]
	v_cndmask_b32_e64 v67, v138, v67, s[84:85]
	v_mul_f32_e32 v68, 0x3e000000, v76
	v_mul_f32_e32 v69, 0x3e000000, v77
	v_max3_f32 v70, v70, v96, v97
	v_cndmask_b32_e64 v54, v51, v138, s[0:1]
	v_mul_f32_e32 v51, 0x3e000000, v55
	v_cndmask_b32_e64 v68, v138, v68, s[82:83]
	v_cndmask_b32_e64 v69, v138, v69, s[80:81]
	v_max3_f32 v70, v70, v66, v67
	v_mul_f32_e32 v71, 0x3e000000, v78
	v_mul_f32_e32 v72, 0x3e000000, v79
	v_cndmask_b32_e64 v55, v51, v138, s[0:1]
	v_mul_f32_e32 v51, 0x3e000000, v56
	v_max3_f32 v70, v70, v68, v69
	v_cndmask_b32_e64 v71, v138, v71, s[78:79]
	v_cndmask_b32_e64 v72, v138, v72, s[76:77]
	v_mul_f32_e32 v73, 0x3e000000, v80
	v_mul_f32_e32 v74, 0x3e000000, v81
	v_cndmask_b32_e64 v56, v51, v138, s[0:1]
	v_mul_f32_e32 v51, 0x3e000000, v57
	v_max3_f32 v70, v70, v71, v72
	v_cndmask_b32_e64 v73, v138, v73, s[70:71]
	v_cndmask_b32_e64 v74, v138, v74, s[68:69]
	v_cndmask_b32_e64 v57, v51, v138, s[0:1]
	v_mul_f32_e32 v51, 0x3e000000, v58
	v_max3_f32 v70, v70, v73, v74
	v_cndmask_b32_e64 v76, v50, v138, s[0:1]
	v_cndmask_b32_e64 v58, v51, v138, s[0:1]
	v_mul_f32_e32 v51, 0x3e000000, v59
	v_max3_f32 v50, v70, v75, v76
	v_cndmask_b32_e64 v59, v51, v138, s[0:1]
	v_mul_f32_e32 v51, 0x3e000000, v60
	v_max3_f32 v50, v50, v52, v53
	v_cndmask_b32_e64 v60, v51, v138, s[0:1]
	v_mul_f32_e32 v51, 0x3e000000, v61
	v_max3_f32 v50, v50, v54, v55
	v_cndmask_b32_e64 v61, v51, v138, s[0:1]
	v_mul_f32_e32 v51, 0x3e000000, v62
	v_max3_f32 v50, v50, v56, v57
	v_cndmask_b32_e64 v62, v51, v138, s[0:1]
	v_mul_f32_e32 v51, 0x3e000000, v63
	v_max3_f32 v50, v50, v58, v59
	v_cndmask_b32_e64 v63, v51, v138, s[0:1]
	v_mul_f32_e32 v51, 0x3e000000, v64
	v_max3_f32 v50, v50, v60, v61
	v_cndmask_b32_e64 v64, v51, v138, s[0:1]
	v_mul_f32_e32 v51, 0x3e000000, v65
	v_max3_f32 v50, v50, v62, v63
	v_cndmask_b32_e64 v65, v51, v138, s[0:1]
	v_max3_f32 v50, v50, v64, v65
	v_max3_f32 v50, v50, v18, v19
	v_max3_f32 v50, v50, v20, v21
	v_max3_f32 v50, v50, v22, v23
	v_max3_f32 v50, v50, v24, v25
	v_max3_f32 v50, v50, v26, v27
	v_max3_f32 v50, v50, v28, v29
	v_cndmask_b32_e64 v30, v30, v138, s[0:1]
	v_cndmask_b32_e64 v31, v31, v138, s[0:1]
	v_mul_f32_e32 v32, 0x3e000000, v32
	v_mul_f32_e32 v33, 0x3e000000, v33
	v_max3_f32 v50, v50, v30, v31
	v_cndmask_b32_e64 v32, v32, v138, s[0:1]
	v_cndmask_b32_e64 v33, v33, v138, s[0:1]
	v_mul_f32_e32 v77, 0x3e000000, v14
	v_mul_f32_e32 v14, 0x3e000000, v34
	v_max3_f32 v50, v50, v32, v33
	v_mul_f32_e32 v2, 0x3e000000, v2
	v_mul_f32_e32 v3, 0x3e000000, v3
	v_cndmask_b32_e64 v81, v138, v14, s[36:37]
	v_mul_f32_e32 v14, 0x3e000000, v35
	v_max3_f32 v50, v50, v2, v3
	v_mul_f32_e32 v4, 0x3e000000, v4
	v_mul_f32_e32 v5, 0x3e000000, v5
	v_cndmask_b32_e64 v82, v138, v14, s[38:39]
	v_mul_f32_e32 v14, 0x3e000000, v36
	v_max3_f32 v50, v50, v4, v5
	v_mul_f32_e32 v6, 0x3e000000, v6
	v_mul_f32_e32 v7, 0x3e000000, v7
	v_cndmask_b32_e64 v83, v138, v14, s[40:41]
	v_mul_f32_e32 v14, 0x3e000000, v37
	v_max3_f32 v50, v50, v6, v7
	v_mul_f32_e32 v8, 0x3e000000, v8
	v_mul_f32_e32 v9, 0x3e000000, v9
	v_cndmask_b32_e64 v84, v138, v14, s[42:43]
	v_mul_f32_e32 v14, 0x3e000000, v38
	v_max3_f32 v50, v50, v8, v9
	v_mul_f32_e32 v10, 0x3e000000, v10
	v_mul_f32_e32 v11, 0x3e000000, v11
	v_cndmask_b32_e64 v85, v138, v14, s[44:45]
	v_mul_f32_e32 v14, 0x3e000000, v39
	v_max3_f32 v50, v50, v10, v11
	v_mul_f32_e32 v12, 0x3e000000, v12
	v_mul_f32_e32 v70, 0x3e000000, v13
	v_cndmask_b32_e64 v86, v138, v14, s[46:47]
	v_mul_f32_e32 v14, 0x3e000000, v40
	v_max3_f32 v13, v50, v12, v70
	v_mul_f32_e32 v78, 0x3e000000, v15
	v_cndmask_b32_e64 v87, v138, v14, s[48:49]
	v_mul_f32_e32 v14, 0x3e000000, v41
	v_max3_f32 v13, v13, v77, v78
	v_mul_f32_e32 v79, 0x3e000000, v16
	v_mul_f32_e32 v80, 0x3e000000, v17
	v_cndmask_b32_e64 v51, v138, v14, s[50:51]
	v_mul_f32_e32 v14, 0x3e000000, v42
	v_max3_f32 v13, v13, v79, v80
	v_cndmask_b32_e64 v50, v138, v14, s[52:53]
	v_mul_f32_e32 v14, 0x3e000000, v43
	v_max3_f32 v13, v13, v81, v82
	v_cndmask_b32_e64 v42, v138, v14, s[54:55]
	v_mul_f32_e32 v14, 0x3e000000, v44
	v_max3_f32 v13, v13, v83, v84
	v_cndmask_b32_e64 v43, v138, v14, s[56:57]
	v_mul_f32_e32 v14, 0x3e000000, v45
	v_max3_f32 v13, v13, v85, v86
	v_cndmask_b32_e64 v39, v138, v14, s[58:59]
	v_mul_f32_e32 v14, 0x3e000000, v46
	v_max3_f32 v13, v13, v87, v51
	v_cndmask_b32_e64 v40, v138, v14, s[60:61]
	v_mul_f32_e32 v14, 0x3e000000, v47
	v_max3_f32 v13, v13, v50, v42
	v_cndmask_b32_e64 v41, v138, v14, s[62:63]
	v_mul_f32_e32 v14, 0x3e000000, v48
	v_max3_f32 v13, v13, v43, v39
	v_cndmask_b32_e64 v38, v138, v14, s[64:65]
	v_mul_f32_e32 v14, 0x3e000000, v49
	v_max3_f32 v13, v13, v40, v41
	v_cndmask_b32_e64 v34, v138, v14, s[66:67]
	v_max3_f32 v13, v13, v38, v34
	ds_bpermute_b32 v14, v130, v13
	s_add_i32 s8, s20, 1
	v_readlane_b32 s87, v254, 12
	s_waitcnt lgkmcnt(0)
; __device__ __forceinline__ unsigned cvt_pk_bf16(float lo, float hi) { unsigned r; asm volatile("v_cvt_pk_bf16_f32 %0, %1, %2" : "=v"(r) : "v"(lo), "v"(hi)); return r; }
; #define LAS __attribute__((address_space(3)))
; __device__ __forceinline__ void attn_unit(LAS unsigned char* lds, const bf16_t* Q, bf16_t* O, const bf16_t* Kb, const bf16_t* Vb, const float* sinks, int unit, int tid, int lane, int wid, int chain_ui) {
;     ...
;         mx = fmaxf(mx, __shfl_xor(mx, 32)); mx = fmaxf(mx, sink);
;         const float L2E = 1.4426950408889634f, mneg = -mx * L2E;
;         float sum = 0.f;
; #pragma unroll
;         for (int j = 0; j < 5; ++j)
; #pragma unroll
;             for (int r = 0; r < 16; ++r) { const float pv = __builtin_amdgcn_exp2f(S[j][r] * L2E + mneg); S[j][r] = pv; sum += pv; }
;         sum += __shfl_xor(sum, 32);
;         const float inv = 1.0f / (sum + __builtin_amdgcn_exp2f((sink - mx) * L2E));
;         f32x16 O0, O1;
; #pragma unroll
;         for (int r = 0; r < 16; ++r) { O0[r] = 0.f; O1[r] = 0.f; }
; #pragma unroll
;         for (int j = 0; j < 5; ++j)
; #pragma unroll
;             for (int st = 0; st < 2; ++st) {
;                 u32x4 pw; pw.x = pg8::cvt_pk_bf16(S[j][8 * st + 0], S[j][8 * st + 1]); pw.y = pg8::cvt_pk_bf16(S[j][8 * st + 2], S[j][8 * st + 3]);
;                 pw.z = pg8::cvt_pk_bf16(S[j][8 * st + 4], S[j][8 * st + 5]); pw.w = pg8::cvt_pk_bf16(S[j][8 * st + 6], S[j][8 * st + 7]);
;                 const bf16x8 Pf = __builtin_bit_cast(bf16x8, pw);
;                 const int kvoff = ((((rb + j) >> 2) ? ph1 : ph0) + ((32 * (rb + j)) & 127) + 16 * st + 8 * hi) * 2;
;                 const bf16x8 V0 = *(const LAS bf16x8*)(lds + VS_OFF + q * VS_PITCH + kvoff), V1 = *(const LAS bf16x8*)(lds + VS_OFF + (32 + q) * VS_PITCH + kvoff);
;                 O0 = __builtin_amdgcn_mfma_f32_32x32x16_bf16(V0, Pf, O0, 0, 0, 0); O1 = __builtin_amdgcn_mfma_f32_32x32x16_bf16(V1, Pf, O1, 0, 0, 0); }
	v_max3_f32 v35, v13, v14, v141
	v_pk_mul_f32 v[36:37], v[34:35], s[10:11] op_sel_hi:[1,0]
	s_add_i32 s11, s11, s16
	v_fma_f32 v13, v100, s10, -v37
	v_exp_f32_e32 v13, v13
	v_fma_f32 v14, v111, s10, -v37
	v_exp_f32_e32 v14, v14
	v_fma_f32 v16, v139, s10, -v37
	v_exp_f32_e32 v16, v16
	v_fma_f32 v17, v140, s10, -v37
	v_exp_f32_e32 v17, v17
	v_fma_f32 v34, v94, s10, -v37
	v_add_f32_e32 v15, 0, v13
	v_exp_f32_e32 v34, v34
	v_fma_f32 v44, v95, s10, -v37
	v_add_f32_e32 v15, v14, v15
	v_exp_f32_e32 v44, v44
	v_fma_f32 v45, v96, s10, -v37
	v_add_f32_e32 v15, v16, v15
	v_exp_f32_e32 v45, v45
	v_fma_f32 v46, v97, s10, -v37
	v_add_f32_e32 v15, v17, v15
	v_exp_f32_e32 v46, v46
	v_fma_f32 v47, v66, s10, -v37
	v_add_f32_e32 v15, v34, v15
	v_exp_f32_e32 v47, v47
	v_fma_f32 v48, v67, s10, -v37
	v_add_f32_e32 v15, v44, v15
	v_exp_f32_e32 v48, v48
	v_fma_f32 v49, v68, s10, -v37
	v_add_f32_e32 v15, v45, v15
	v_exp_f32_e32 v49, v49
	v_fma_f32 v66, v69, s10, -v37
	v_add_f32_e32 v15, v46, v15
	v_exp_f32_e32 v66, v66
	v_fma_f32 v67, v71, s10, -v37
	v_add_f32_e32 v15, v47, v15
	v_exp_f32_e32 v67, v67
	v_fma_f32 v68, v72, s10, -v37
	v_add_f32_e32 v15, v48, v15
	v_exp_f32_e32 v68, v68
	v_fma_f32 v69, v73, s10, -v37
	v_add_f32_e32 v15, v49, v15
	v_exp_f32_e32 v69, v69
	v_fma_f32 v71, v74, s10, -v37
	v_add_f32_e32 v15, v66, v15
	v_exp_f32_e32 v71, v71
	v_fma_f32 v72, v75, s10, -v37
	v_add_f32_e32 v15, v67, v15
	v_exp_f32_e32 v72, v72
	v_fma_f32 v73, v76, s10, -v37
	v_add_f32_e32 v15, v68, v15
	v_exp_f32_e32 v73, v73
	v_fma_f32 v52, v52, s10, -v37
	v_add_f32_e32 v15, v69, v15
	v_exp_f32_e32 v74, v52
	v_fma_f32 v52, v53, s10, -v37
	v_add_f32_e32 v15, v71, v15
	v_exp_f32_e32 v75, v52
	v_fma_f32 v52, v54, s10, -v37
	v_add_f32_e32 v15, v72, v15
	v_exp_f32_e32 v76, v52
	v_fma_f32 v52, v55, s10, -v37
	v_add_f32_e32 v15, v73, v15
	v_exp_f32_e32 v88, v52
	v_fma_f32 v52, v56, s10, -v37
	v_add_f32_e32 v15, v74, v15
	v_exp_f32_e32 v89, v52
	v_fma_f32 v52, v57, s10, -v37
	v_add_f32_e32 v15, v75, v15
	v_exp_f32_e32 v90, v52
	v_fma_f32 v52, v58, s10, -v37
	v_add_f32_e32 v15, v76, v15
	v_exp_f32_e32 v91, v52
	v_fma_f32 v52, v59, s10, -v37
	v_add_f32_e32 v15, v88, v15
	v_exp_f32_e32 v92, v52
	v_fma_f32 v52, v60, s10, -v37
	v_add_f32_e32 v15, v89, v15
	v_exp_f32_e32 v93, v52
	v_fma_f32 v52, v61, s10, -v37
	v_add_f32_e32 v15, v90, v15
	v_exp_f32_e32 v94, v52
	v_fma_f32 v52, v62, s10, -v37
	v_add_f32_e32 v15, v91, v15
	v_exp_f32_e32 v95, v52
	v_fma_f32 v52, v63, s10, -v37
	v_add_f32_e32 v15, v92, v15
	v_exp_f32_e32 v96, v52
	v_fma_f32 v52, v64, s10, -v37
	v_add_f32_e32 v15, v93, v15
	v_exp_f32_e32 v64, v52
	v_fma_f32 v52, v65, s10, -v37
	v_add_f32_e32 v15, v94, v15
	v_exp_f32_e32 v65, v52
	v_fma_f32 v18, v18, s10, -v37
	v_add_f32_e32 v15, v95, v15
	v_exp_f32_e32 v97, v18
	v_fma_f32 v18, v19, s10, -v37
	v_add_f32_e32 v15, v96, v15
	v_exp_f32_e32 v100, v18
	v_fma_f32 v18, v20, s10, -v37
	v_add_f32_e32 v15, v64, v15
	v_exp_f32_e32 v111, v18
	v_fma_f32 v18, v21, s10, -v37
	v_add_f32_e32 v15, v65, v15
	v_exp_f32_e32 v139, v18
	v_fma_f32 v18, v22, s10, -v37
	v_add_f32_e32 v15, v97, v15
	v_exp_f32_e32 v140, v18
	v_fma_f32 v18, v23, s10, -v37
	v_add_f32_e32 v15, v100, v15
	v_exp_f32_e32 v150, v18
	v_fma_f32 v18, v24, s10, -v37
	v_add_f32_e32 v15, v111, v15
	v_exp_f32_e32 v151, v18
	v_fma_f32 v18, v25, s10, -v37
	v_add_f32_e32 v15, v139, v15
	v_exp_f32_e32 v152, v18
	v_fma_f32 v18, v26, s10, -v37
	v_add_f32_e32 v15, v140, v15
	v_exp_f32_e32 v153, v18
	v_fma_f32 v18, v27, s10, -v37
	v_add_f32_e32 v15, v150, v15
	v_exp_f32_e32 v154, v18
	v_fma_f32 v18, v28, s10, -v37
	v_add_f32_e32 v15, v151, v15
	v_exp_f32_e32 v155, v18
	v_fma_f32 v18, v29, s10, -v37
	v_add_f32_e32 v15, v152, v15
	v_exp_f32_e32 v156, v18
	v_fma_f32 v18, v30, s10, -v37
	v_add_f32_e32 v15, v153, v15
	v_exp_f32_e32 v157, v18
	v_fma_f32 v18, v31, s10, -v37
	v_add_f32_e32 v15, v154, v15
	v_exp_f32_e32 v158, v18
	v_fma_f32 v18, v32, s10, -v37
	v_add_f32_e32 v15, v155, v15
	v_exp_f32_e32 v159, v18
	v_fma_f32 v18, v33, s10, -v37
	v_add_f32_e32 v15, v156, v15
	v_exp_f32_e32 v160, v18
	v_fma_f32 v2, v2, s10, -v37
	v_add_f32_e32 v15, v157, v15
	v_exp_f32_e32 v161, v2
	v_fma_f32 v2, v3, s10, -v37
	v_add_f32_e32 v15, v158, v15
	v_exp_f32_e32 v162, v2
	v_fma_f32 v3, v4, s10, -v37
	v_add_f32_e32 v2, v159, v15
	v_exp_f32_e32 v163, v3
	v_fma_f32 v3, v5, s10, -v37
	v_add_f32_e32 v2, v160, v2
	v_exp_f32_e32 v164, v3
	v_fma_f32 v3, v6, s10, -v37
	v_add_f32_e32 v2, v161, v2
	v_exp_f32_e32 v165, v3
	v_fma_f32 v3, v7, s10, -v37
	v_add_f32_e32 v2, v162, v2
	v_exp_f32_e32 v166, v3
	v_add_f32_e32 v2, v163, v2
	v_add_f32_e32 v2, v164, v2
	v_add_f32_e32 v2, v165, v2
	v_add_f32_e32 v6, v166, v2
	v_fma_f32 v2, v8, s10, -v37
	v_exp_f32_e32 v167, v2
	v_fma_f32 v2, v9, s10, -v37
	v_exp_f32_e32 v168, v2
	v_fma_f32 v2, v10, s10, -v37
	v_exp_f32_e32 v169, v2
	v_cvt_pk_bf16_f32 v18, v13, v14
	v_cvt_pk_bf16_f32 v19, v16, v17
	v_cvt_pk_bf16_f32 v20, v34, v44
	v_cvt_pk_bf16_f32 v21, v45, v46
	ds_read_b128 v[2:5], v142 offset:36864
	ds_read_b128 v[22:25], v144 offset:36864
	v_add_f32_e32 v6, v167, v6
	v_add_f32_e32 v6, v168, v6
	v_add_f32_e32 v26, v169, v6
	v_fma_f32 v6, v11, s10, -v37
	v_exp_f32_e32 v34, v6
	v_fma_f32 v6, v12, s10, -v37
	v_exp_f32_e32 v170, v6
	v_cvt_pk_bf16_f32 v44, v47, v48
	v_add_f32_e32 v26, v34, v26
	v_cvt_pk_bf16_f32 v45, v49, v66
	v_cvt_pk_bf16_f32 v46, v67, v68
	v_cvt_pk_bf16_f32 v47, v69, v71
	ds_read_b128 v[52:55], v142 offset:36896
	ds_read_b128 v[56:59], v144 offset:36896
	s_waitcnt lgkmcnt(3)
	v_mfma_f32_32x32x16_bf16 v[2:17], v[2:5], v[18:21], 0
	v_add_f32_e32 v171, v170, v26
	v_fma_f32 v48, v70, s10, -v37
	v_exp_f32_e32 v66, v48
	v_fma_f32 v48, v77, s10, -v37
	v_exp_f32_e32 v67, v48
	v_fma_f32 v48, v78, s10, -v37
	v_exp_f32_e32 v68, v48
	s_waitcnt lgkmcnt(2)
; __device__ __forceinline__ unsigned cvt_pk_bf16(float lo, float hi) { unsigned r; asm volatile("v_cvt_pk_bf16_f32 %0, %1, %2" : "=v"(r) : "v"(lo), "v"(hi)); return r; }
; #define LAS __attribute__((address_space(3)))
; __device__ __forceinline__ void attn_unit(LAS unsigned char* lds, const bf16_t* Q, bf16_t* O, const bf16_t* Kb, const bf16_t* Vb, const float* sinks, int unit, int tid, int lane, int wid, int chain_ui) {
;     ...
;             for (int r = 0; r < 16; ++r) { const float pv = __builtin_amdgcn_exp2f(S[j][r] * L2E + mneg); S[j][r] = pv; sum += pv; }
;         sum += __shfl_xor(sum, 32);
;         const float inv = 1.0f / (sum + __builtin_amdgcn_exp2f((sink - mx) * L2E));
;         f32x16 O0, O1;
; #pragma unroll
;         for (int r = 0; r < 16; ++r) { O0[r] = 0.f; O1[r] = 0.f; }
; #pragma unroll
;         for (int j = 0; j < 5; ++j)
; #pragma unroll
;             for (int st = 0; st < 2; ++st) {
;                 u32x4 pw; pw.x = pg8::cvt_pk_bf16(S[j][8 * st + 0], S[j][8 * st + 1]); pw.y = pg8::cvt_pk_bf16(S[j][8 * st + 2], S[j][8 * st + 3]);
;                 pw.z = pg8::cvt_pk_bf16(S[j][8 * st + 4], S[j][8 * st + 5]); pw.w = pg8::cvt_pk_bf16(S[j][8 * st + 6], S[j][8 * st + 7]);
;                 const bf16x8 Pf = __builtin_bit_cast(bf16x8, pw);
;                 const int kvoff = ((((rb + j) >> 2) ? ph1 : ph0) + ((32 * (rb + j)) & 127) + 16 * st + 8 * hi) * 2;
;                 const bf16x8 V0 = *(const LAS bf16x8*)(lds + VS_OFF + q * VS_PITCH + kvoff), V1 = *(const LAS bf16x8*)(lds + VS_OFF + (32 + q) * VS_PITCH + kvoff);
;                 O0 = __builtin_amdgcn_mfma_f32_32x32x16_bf16(V0, Pf, O0, 0, 0, 0); O1 = __builtin_amdgcn_mfma_f32_32x32x16_bf16(V1, Pf, O1, 0, 0, 0); }
	v_mfma_f32_32x32x16_bf16 v[18:33], v[22:25], v[18:21], 0
	v_fma_f32 v48, v79, s10, -v37
	v_exp_f32_e32 v69, v48
	v_fma_f32 v49, v81, s10, -v37
	v_exp_f32_e32 v71, v49
	v_fma_f32 v49, v87, s10, -v37
	v_fma_f32 v42, v42, s10, -v37
	v_fma_f32 v38, v38, s10, -v37
	s_waitcnt lgkmcnt(1)
	v_mfma_f32_32x32x16_bf16 v[2:17], v[52:55], v[44:47], v[2:17]
	v_cvt_pk_bf16_f32 v52, v72, v73
	v_cvt_pk_bf16_f32 v53, v74, v75
	v_cvt_pk_bf16_f32 v54, v76, v88
	v_cvt_pk_bf16_f32 v55, v89, v90
	ds_read_b128 v[60:63], v143 offset:36864
	v_exp_f32_e32 v75, v49
	v_sub_f32_e32 v36, v36, v37
	s_waitcnt lgkmcnt(1)
	v_mfma_f32_32x32x16_bf16 v[18:33], v[56:59], v[44:47], v[18:33]
	v_add_f32_e32 v44, v66, v171
	v_add_f32_e32 v44, v67, v44
	v_add_f32_e32 v44, v68, v44
	v_add_f32_e32 v48, v69, v44
	v_fma_f32 v44, v80, s10, -v37
	v_exp_f32_e32 v70, v44
	ds_read_b128 v[44:47], v146 offset:36864
	s_waitcnt lgkmcnt(0)
	v_mfma_f32_32x32x16_bf16 v[18:33], v[44:47], v[52:55], v[18:33]
	v_add_f32_e32 v44, v70, v48
	v_add_f32_e32 v48, v71, v44
	v_fma_f32 v44, v82, s10, -v37
	v_cvt_pk_bf16_f32 v56, v91, v92
	v_cvt_pk_bf16_f32 v57, v93, v94
	v_cvt_pk_bf16_f32 v58, v95, v96
	v_cvt_pk_bf16_f32 v59, v64, v65
	v_exp_f32_e32 v64, v44
	v_fma_f32 v44, v83, s10, -v37
	v_mfma_f32_32x32x16_bf16 v[2:17], v[60:63], v[52:55], v[2:17]
	ds_read_b128 v[60:63], v143 offset:36896
	v_exp_f32_e32 v65, v44
	ds_read_b128 v[44:47], v146 offset:36896
	v_cvt_pk_bf16_f32 v52, v97, v100
	v_cvt_pk_bf16_f32 v53, v111, v139
	v_cvt_pk_bf16_f32 v54, v140, v150
	v_cvt_pk_bf16_f32 v55, v151, v152
	s_waitcnt lgkmcnt(0)
	v_mfma_f32_32x32x16_bf16 v[18:33], v[44:47], v[56:59], v[18:33]
	v_fma_f32 v44, v84, s10, -v37
	v_exp_f32_e32 v72, v44
	v_fma_f32 v44, v85, s10, -v37
	v_exp_f32_e32 v73, v44
	v_fma_f32 v44, v86, s10, -v37
	v_exp_f32_e32 v74, v44
	ds_read_b128 v[44:47], v148 offset:36864
	v_mfma_f32_32x32x16_bf16 v[2:17], v[60:63], v[56:59], v[2:17]
	ds_read_b128 v[60:63], v145 offset:36864
	v_add_f32_e32 v48, v64, v48
	v_add_f32_e32 v48, v65, v48
	v_cvt_pk_bf16_f32 v56, v153, v154
	v_cvt_pk_bf16_f32 v57, v155, v156
	v_cvt_pk_bf16_f32 v58, v157, v158
	v_cvt_pk_bf16_f32 v59, v159, v160
	s_waitcnt lgkmcnt(1)
	v_mfma_f32_32x32x16_bf16 v[18:33], v[44:47], v[52:55], v[18:33]
	v_add_f32_e32 v44, v72, v48
	v_add_f32_e32 v44, v73, v44
	v_add_f32_e32 v44, v74, v44
	v_add_f32_e32 v76, v75, v44
	v_fma_f32 v44, v51, s10, -v37
	v_exp_f32_e32 v77, v44
	ds_read_b128 v[44:47], v148 offset:36896
	s_waitcnt lgkmcnt(1)
	v_mfma_f32_32x32x16_bf16 v[2:17], v[60:63], v[52:55], v[2:17]
	ds_read_b128 v[60:63], v145 offset:36896
	v_fma_f32 v48, v50, s10, -v37
	v_exp_f32_e32 v36, v36
	s_waitcnt lgkmcnt(0)
	v_mfma_f32_32x32x16_bf16 v[2:17], v[60:63], v[56:59], v[2:17]
	v_exp_f32_e32 v60, v48
	v_cvt_pk_bf16_f32 v48, v161, v162
	v_cvt_pk_bf16_f32 v49, v163, v164
	v_cvt_pk_bf16_f32 v50, v165, v166
	v_cvt_pk_bf16_f32 v51, v167, v168
	ds_read_b128 v[52:55], v147 offset:36864
	v_exp_f32_e32 v61, v42
	v_mfma_f32_32x32x16_bf16 v[18:33], v[44:47], v[56:59], v[18:33]
	v_add_f32_e32 v44, v77, v76
	v_fma_f32 v42, v43, s10, -v37
	v_add_f32_e32 v46, v60, v44
	v_exp_f32_e32 v62, v42
	ds_read_b128 v[42:45], v149 offset:36864
	v_add_f32_e32 v46, v61, v46
	v_add_f32_e32 v63, v62, v46
	s_waitcnt lgkmcnt(1)
	v_mfma_f32_32x32x16_bf16 v[2:17], v[52:55], v[48:51], v[2:17]
	v_cvt_pk_bf16_f32 v52, v169, v34
	v_fma_f32 v34, v39, s10, -v37
	v_fma_f32 v39, v40, s10, -v37
	v_cvt_pk_bf16_f32 v53, v170, v66
	v_cvt_pk_bf16_f32 v54, v67, v68
	v_cvt_pk_bf16_f32 v55, v69, v70
	ds_read_b128 v[56:59], v147 offset:36896
	s_waitcnt lgkmcnt(1)
	v_mfma_f32_32x32x16_bf16 v[18:33], v[42:45], v[48:51], v[18:33]
	v_exp_f32_e32 v66, v39
	v_fma_f32 v39, v41, s10, -v37
	ds_read_b128 v[40:43], v149 offset:36896
	v_exp_f32_e32 v34, v34
	v_exp_f32_e32 v67, v39
	v_lshl_or_b32 v39, s2, 1, v128
	v_cvt_pk_bf16_f32 v44, v71, v64
	s_waitcnt lgkmcnt(1)
	v_mfma_f32_32x32x16_bf16 v[2:17], v[56:59], v[52:55], v[2:17]
	v_add_u32_e32 v56, v131, v39
	v_cvt_pk_bf16_f32 v45, v65, v72
	v_cvt_pk_bf16_f32 v46, v73, v74
	v_cvt_pk_bf16_f32 v47, v75, v77
	ds_read_b128 v[48:51], v56 offset:36864
	v_add_u32_e32 v57, v132, v39
	s_waitcnt lgkmcnt(1)
	v_mfma_f32_32x32x16_bf16 v[18:33], v[40:43], v[52:55], v[18:33]
	v_add_f32_e32 v40, v34, v63
	v_add_f32_e32 v40, v66, v40
	v_add_f32_e32 v42, v67, v40
	v_exp_f32_e32 v43, v38
	ds_read_b128 v[38:41], v57 offset:36864
	s_waitcnt lgkmcnt(1)
	v_mfma_f32_32x32x16_bf16 v[2:17], v[48:51], v[44:47], v[2:17]
	v_cvt_pk_bf16_f32 v48, v60, v61
	v_cvt_pk_bf16_f32 v49, v62, v34
	v_add_f32_e32 v34, v43, v42
	v_cvt_pk_bf16_f32 v50, v66, v67
	v_cvt_pk_bf16_f32 v51, v43, v36
	ds_read_b128 v[52:55], v56 offset:36896
	s_waitcnt lgkmcnt(1)
	v_mfma_f32_32x32x16_bf16 v[18:33], v[38:41], v[44:47], v[18:33]
	v_add_f32_e32 v38, v36, v34
	ds_bpermute_b32 v39, v130, v38
	v_sub_f32_e32 v34, v141, v35
	v_mul_f32_e32 v34, 0x3fb8aa3b, v34
	v_exp_f32_e32 v40, v34
	ds_read_b128 v[34:37], v57 offset:36896
	s_waitcnt lgkmcnt(1)
	v_add_f32_e32 v38, v38, v39
	v_mfma_f32_32x32x16_bf16 v[2:17], v[52:55], v[48:51], v[2:17]
	v_add_f32_e32 v38, v40, v38
	v_div_scale_f32 v39, s[0:1], v38, v38, 1.0
	v_rcp_f32_e32 v40, v39
	s_or_b32 s0, s21, s14
	s_ashr_i32 s1, s0, 31
	s_lshl_b64 s[0:1], s[0:1], 11
	s_waitcnt lgkmcnt(0)
; __device__ __forceinline__ void attn_unit(LAS unsigned char* lds, const bf16_t* Q, bf16_t* O, const bf16_t* Kb, const bf16_t* Vb, const float* sinks, int unit, int tid, int lane, int wid, int chain_ui) {
;     const int n = unit & 63, g = (unit >> 6) & 3, b = unit >> 8;
;     const int r0 = b * SEQ + n * 128;
;     const int q = lane & 31, hi = lane >> 5, hq = wid >> 1, head = 4 * g + hq;
;     bf16x8 Qf[2][4];
; #pragma unroll
;     for (int it = 0; it < 2; ++it) { const bf16_t* qp = Q + (size_t)(r0 + 32 * ((wid & 1) * 2 + it) + q) * DM + head * 64;
; #pragma unroll
;         for (int d0 = 0; d0 < 4; ++d0) Qf[it][d0] = *(const bf16x8*)(qp + 16 * d0 + 8 * hi); }
;     const bool full = chain_ui <= 0; const int par = full ? 0 : (chain_ui & 1);
;     const int ph0 = par * 128, ph1 = (par ^ 1) * 128;
;     u32x4 kk[4], vv[4];
; #pragma unroll
;     for (int i = 0; i < 4; ++i) { const int t_ = tid + 512 * (i & 1), krl = t_ >> 3, ch = t_ & 7, h = (i < 2) ? 1 : 0;
;         kk[i] = (u32x4){0u, 0u, 0u, 0u};
;         if (h == 1 || (full && n > 0)) kk[i] = *(const u32x4*)(Kb + (size_t)(r0 - 128 + h * 128 + krl) * 256 + g * 64 + ch * 8); }
; #pragma unroll
;     for (int i = 0; i < 4; ++i) { const int t_ = tid + 512 * (i & 1), kvl = t_ & 127, c = t_ >> 7, h = (i < 2) ? 1 : 0;
;     ...
;         { LAS unsigned char* ost = lds + OS_OFF + wid * OS_WAVE;
; #pragma unroll
;           for (int r4 = 0; r4 < 4; ++r4) { const int d = 8 * r4 + 4 * hi;
;             u32x2 w0, w1; w0.x = pg8::cvt_pk_bf16(O0[4 * r4] * inv, O0[4 * r4 + 1] * inv); w0.y = pg8::cvt_pk_bf16(O0[4 * r4 + 2] * inv, O0[4 * r4 + 3] * inv);
;             w1.x = pg8::cvt_pk_bf16(O1[4 * r4] * inv, O1[4 * r4 + 1] * inv); w1.y = pg8::cvt_pk_bf16(O1[4 * r4 + 2] * inv, O1[4 * r4 + 3] * inv);
;             *(LAS u32x2*)(ost + q * OS_PITCH + d * 2) = w0; *(LAS u32x2*)(ost + q * OS_PITCH + (32 + d) * 2) = w1; }
;           __builtin_amdgcn_wave_barrier(); asm volatile("" ::: "memory");
;           bf16_t* ob = O + (size_t)(r0 + 32 * rb) * DM + head * 64;
; #pragma unroll
;           for (int ps = 0; ps < 4; ++ps) { const int rr = 8 * ps + (lane >> 3), pc = lane & 7;
;             const u32x4 v = *(const LAS u32x4*)(ost + rr * OS_PITCH + pc * 16);
;             *(u32x4*)(ob + (size_t)rr * DM + pc * 8) = v; }
;           __builtin_amdgcn_wave_barrier(); asm volatile("" ::: "memory"); }
;     }
;     __syncthreads();
	v_mfma_f32_32x32x16_bf16 v[18:33], v[34:37], v[48:51], v[18:33]
	v_fma_f32 v34, -v39, v40, 1.0
	v_fmac_f32_e32 v40, v34, v40
	v_div_scale_f32 v34, vcc, 1.0, v38, 1.0
	v_mul_f32_e32 v35, v34, v40
	v_fma_f32 v36, -v39, v35, v34
	v_fmac_f32_e32 v35, v36, v40
	v_fma_f32 v34, -v39, v35, v34
	v_div_fmas_f32 v34, v34, v40, v35
	v_div_fixup_f32 v34, v34, v38, 1.0
	v_mul_f32_e32 v2, v2, v34
	v_mul_f32_e32 v3, v3, v34
	v_cvt_pk_bf16_f32 v2, v2, v3
	v_mul_f32_e32 v3, v4, v34
	v_mul_f32_e32 v4, v5, v34
	v_cvt_pk_bf16_f32 v3, v3, v4
	v_mul_f32_e32 v4, v18, v34
	v_mul_f32_e32 v5, v19, v34
	v_cvt_pk_bf16_f32 v4, v4, v5
	v_mul_f32_e32 v5, v20, v34
	v_mul_f32_e32 v18, v21, v34
	v_cvt_pk_bf16_f32 v5, v5, v18
	ds_write2_b64 v135, v[2:3], v[4:5] offset1:8
	v_mul_f32_e32 v2, v6, v34
	v_mul_f32_e32 v3, v7, v34
	v_cvt_pk_bf16_f32 v2, v2, v3
	v_mul_f32_e32 v3, v8, v34
	v_mul_f32_e32 v4, v9, v34
	v_cvt_pk_bf16_f32 v3, v3, v4
	v_mul_f32_e32 v4, v22, v34
	v_mul_f32_e32 v5, v23, v34
	v_cvt_pk_bf16_f32 v4, v4, v5
	v_mul_f32_e32 v5, v24, v34
	v_mul_f32_e32 v6, v25, v34
	v_cvt_pk_bf16_f32 v5, v5, v6
	ds_write2_b64 v135, v[2:3], v[4:5] offset0:2 offset1:10
	v_mul_f32_e32 v2, v10, v34
	v_mul_f32_e32 v3, v11, v34
	v_cvt_pk_bf16_f32 v2, v2, v3
	v_mul_f32_e32 v3, v12, v34
	v_mul_f32_e32 v4, v13, v34
	v_cvt_pk_bf16_f32 v3, v3, v4
	v_mul_f32_e32 v4, v26, v34
	v_mul_f32_e32 v5, v27, v34
	v_cvt_pk_bf16_f32 v4, v4, v5
	v_mul_f32_e32 v5, v28, v34
	v_mul_f32_e32 v6, v29, v34
	v_cvt_pk_bf16_f32 v5, v5, v6
	ds_write2_b64 v135, v[2:3], v[4:5] offset0:4 offset1:12
	v_mul_f32_e32 v2, v14, v34
	v_mul_f32_e32 v3, v15, v34
	v_cvt_pk_bf16_f32 v2, v2, v3
	v_mul_f32_e32 v3, v16, v34
	v_mul_f32_e32 v4, v17, v34
	v_cvt_pk_bf16_f32 v3, v3, v4
	v_mul_f32_e32 v4, v30, v34
	v_mul_f32_e32 v5, v31, v34
	v_cvt_pk_bf16_f32 v4, v4, v5
	v_mul_f32_e32 v5, v32, v34
	v_mul_f32_e32 v6, v33, v34
	v_cvt_pk_bf16_f32 v5, v5, v6
	ds_write2_b64 v135, v[2:3], v[4:5] offset0:6 offset1:14
	ds_read_b128 v[2:5], v136
	ds_read_b128 v[6:9], v137
	v_lshl_add_u64 v[14:15], v[120:121], 0, s[0:1]
	v_lshl_add_u64 v[10:11], v[14:15], 0, v[112:113]
	v_lshl_add_u64 v[16:17], v[14:15], 0, v[114:115]
	s_waitcnt lgkmcnt(1)
	global_store_dwordx4 v[10:11], v[2:5], off
	ds_read_b128 v[2:5], v137 offset:1152
	ds_read_b128 v[10:13], v137 offset:2304
	s_cmpk_lt_i32 s11, 0x400
	s_waitcnt lgkmcnt(2)
	global_store_dwordx4 v[16:17], v[6:9], off
	s_cselect_b64 s[0:1], -1, 0
	s_cmp_lt_u32 s20, 3
	v_lshl_add_u64 v[6:7], v[14:15], 0, v[116:117]
	s_waitcnt lgkmcnt(1)
	global_store_dwordx4 v[6:7], v[2:5], off
	s_cselect_b64 s[2:3], -1, 0
	s_or_b64 s[2:3], s[6:7], s[2:3]
	v_lshl_add_u64 v[2:3], v[14:15], 0, v[118:119]
	s_waitcnt lgkmcnt(0)
	global_store_dwordx4 v[2:3], v[10:13], off
	s_and_b64 s[0:1], s[0:1], s[2:3]
	s_add_i32 s17, s17, s18
	s_and_b64 vcc, exec, s[0:1]
	s_mov_b32 s20, s8
	s_barrier
	s_cbranch_vccz .LBB0_652
.LBB0_639:
	s_and_b64 s[0:1], exec, s[6:7]
	s_cselect_b32 s74, 0, s20
	s_and_b32 s22, s11, 63
	s_bfe_u32 s72, s11, 0x20006
	s_and_b32 s0, s17, 0xffffe000
	s_lshl_b32 s1, s22, 7
	s_or_b32 s21, s0, s1
	s_lshl_b32 s23, s72, 2
	v_readlane_b32 s0, v254, 0
	s_add_i32 s23, s23, s0
	v_or_b32_e32 v6, s21, v1
	s_lshl_b32 s0, s23, 7
	s_add_u32 s68, s25, s0
	v_readlane_b32 s0, v254, 13
	v_or_b32_e32 v4, s5, v6
	s_addc_u32 s69, s0, 0
	v_lshlrev_b32_e32 v100, 1, v98
	v_ashrrev_i32_e32 v5, 31, v4
	v_lshl_add_u64 v[2:3], s[68:69], 0, v[100:101]
	v_lshlrev_b64 v[4:5], 11, v[4:5]
	v_lshl_add_u64 v[4:5], v[2:3], 0, v[4:5]
	global_load_dwordx4 v[62:65], v[4:5], off
	global_load_dwordx4 v[58:61], v[4:5], off offset:32
	global_load_dwordx4 v[54:57], v[4:5], off offset:64
	global_load_dwordx4 v[50:53], v[4:5], off offset:96
	v_lshl_add_u64 v[180:181], v[4:5], 0, s[98:99]
	v_or_b32_e32 v4, s14, v6
	v_ashrrev_i32_e32 v5, 31, v4
	v_lshlrev_b64 v[4:5], 11, v[4:5]
	v_lshl_add_u64 v[2:3], v[2:3], 0, v[4:5]
	s_cmp_eq_u32 s74, 0
	global_load_dwordx4 v[94:97], v[2:3], off
	global_load_dwordx4 v[90:93], v[2:3], off offset:32
	global_load_dwordx4 v[86:89], v[2:3], off offset:64
	global_load_dwordx4 v[82:85], v[2:3], off offset:96
	v_lshl_add_u64 v[182:183], v[2:3], 0, s[98:99]
	s_cselect_b64 s[70:71], -1, 0
	s_cmp_lg_u32 s22, 0
	v_add_u32_e32 v2, s21, v99
	v_add_u32_e32 v4, s21, v109
	s_cselect_b64 s[0:1], -1, 0
	s_lshl_b32 s8, s72, 7
	v_ashrrev_i32_e32 v3, 31, v2
	v_ashrrev_i32_e32 v5, 31, v4
	v_lshl_add_u64 v[18:19], v[102:103], 0, s[8:9]
	v_lshlrev_b64 v[2:3], 9, v[2:3]
	v_lshlrev_b64 v[4:5], 9, v[4:5]
	v_lshl_add_u64 v[2:3], v[18:19], 0, v[2:3]
	v_lshl_add_u64 v[4:5], v[18:19], 0, v[4:5]
	v_lshl_add_u64 v[184:185], v[2:3], 0, s[100:101]
	v_lshl_add_u64 v[186:187], v[4:5], 0, s[100:101]
	global_load_dwordx4 v[10:13], v[2:3], off
	s_nop 0
	global_load_dwordx4 v[2:5], v[4:5], off
	s_and_b64 s[76:77], s[0:1], s[70:71]
	v_cndmask_b32_e64 v6, 0, 1, s[76:77]
	s_add_i32 s8, s21, 0xffffff80
	v_cmp_ne_u32_e64 s[2:3], 1, v6
	s_andn2_b64 vcc, exec, s[76:77]
	v_mov_b32_e32 v6, 0
	v_mov_b32_e32 v7, 0
	v_mov_b32_e32 v8, 0
	v_mov_b32_e32 v9, 0
	s_cbranch_vccnz .LBB0_641
	v_add_u32_e32 v6, s8, v99
	v_ashrrev_i32_e32 v7, 31, v6
	v_lshlrev_b64 v[6:7], 9, v[6:7]
	v_lshl_add_u64 v[6:7], v[18:19], 0, v[6:7]
	global_load_dwordx4 v[6:9], v[6:7], off

; __device__ __forceinline__ void attn_unit(LAS unsigned char* lds, const bf16_t* Q, bf16_t* O, const bf16_t* Kb, const bf16_t* Vb, const float* sinks, int unit, int tid, int lane, int wid, int chain_ui) {
;     ...
;     for (int i = 0; i < 4; ++i) { const int t_ = tid + 512 * (i & 1), krl = t_ >> 3, ch = t_ & 7, h = (i < 2) ? 1 : 0;
;         kk[i] = (u32x4){0u, 0u, 0u, 0u};
;         if (h == 1 || (full && n > 0)) kk[i] = *(const u32x4*)(Kb + (size_t)(r0 - 128 + h * 128 + krl) * 256 + g * 64 + ch * 8); }
; #pragma unroll
;     for (int i = 0; i < 4; ++i) { const int t_ = tid + 512 * (i & 1), kvl = t_ & 127, c = t_ >> 7, h = (i < 2) ? 1 : 0;
;         vv[i] = (u32x4){0u, 0u, 0u, 0u};
;         if (h == 1 || (full && n > 0)) vv[i] = *(const u32x4*)(Vb + (size_t)(r0 - 128 + h * 128 + kvl) * 256 + g * 64 + c * 8); }
.LBB0_643:
	s_lshl_b32 s8, s72, 6
	v_add_u32_e32 v30, s21, v122
	s_lshl_b32 s8, s8, 1
	v_readlane_b32 s24, v254, 15
	v_add_u32_e32 v18, 0x80, v30
	s_add_u32 s72, s24, s8
	v_readlane_b32 s8, v254, 19
	v_ashrrev_i32_e32 v19, 31, v18
	s_addc_u32 s73, s8, 0
	v_lshlrev_b64 v[18:19], 9, v[18:19]
	v_lshl_add_u64 v[18:19], s[72:73], 0, v[18:19]
	v_lshl_add_u64 v[20:21], v[104:105], 1, v[18:19]
	v_lshl_add_u64 v[18:19], v[106:107], 1, v[18:19]
	v_lshl_add_u64 v[188:189], v[20:21], 0, s[100:101]
	v_lshl_add_u64 v[190:191], v[18:19], 0, s[100:101]
	global_load_dwordx4 v[26:29], v[20:21], off
	global_load_dwordx4 v[22:25], v[18:19], off
	s_and_b64 vcc, exec, s[2:3]
	v_ashrrev_i32_e32 v31, 31, v30
	s_cbranch_vccnz .LBB0_646
	v_lshlrev_b64 v[18:19], 9, v[30:31]
	v_lshl_add_u64 v[18:19], s[72:73], 0, v[18:19]
	v_lshl_add_u64 v[18:19], v[104:105], 1, v[18:19]
	global_load_dwordx4 v[18:21], v[18:19], off
	s_and_b64 vcc, exec, s[2:3]
	s_cbranch_vccz .LBB0_647

; __device__ __forceinline__ u32x4 pack8(const f32x4 a, const f32x4 b) { u32x4 w; w.x = cvt_pk_bf16(a[0], a[1]); w.y = cvt_pk_bf16(a[2], a[3]); w.z = cvt_pk_bf16(b[0], b[1]); w.w = cvt_pk_bf16(b[2], b[3]); return w; }
;     __device__ __forceinline__ void operator()(const f32x4 (&acc)[2][2][4][2], const Unit& u, int wr, int wc, int fr, int fq) const {
;     ...
;                 sq += ((v0[0] * v0[0] + v0[1] * v0[1]) + (v0[2] * v0[2] + v0[3] * v0[3])) + ((v1[0] * v1[0] + v1[1] * v1[1]) + (v1[2] * v1[2] + v1[3] * v1[3]));
;                 if (XS) ps_[bj] = pack8(v0 * cs[bj][0], v1 * cs[bj][1]); }
;             { const size_t seg = (size_t)(row - fr) * DM + u.pn * BM + wc * 64;
;               store_lines(st, pn_[0], pn_[1], fr, fq, xnew + seg, DM);
;               if (XS) store_lines(st, ps_[0], ps_[1], fr, fq, xs + seg, DM); }
;             sq += __shfl_xor(sq, 16); sq += __shfl_xor(sq, 32);
;             if (fq == 0) ssq[(size_t)row * 16 + u.pn * 4 + wc] = sq;
.Lf9a_done:
	ds_bpermute_b32 v197, v255, v196
	ds_bpermute_b32 v205, v255, v204
	ds_bpermute_b32 v213, v255, v212
	ds_bpermute_b32 v221, v255, v220
	ds_bpermute_b32 v229, v255, v228
	ds_bpermute_b32 v237, v255, v236
	ds_bpermute_b32 v245, v255, v244
	ds_bpermute_b32 v131, v255, v130
	s_waitcnt lgkmcnt(0)
	v_add_f32_e32 v196, v196, v197
	v_add_f32_e32 v204, v204, v205
	v_add_f32_e32 v212, v212, v213
	v_add_f32_e32 v220, v220, v221
	v_add_f32_e32 v228, v228, v229
	v_add_f32_e32 v236, v236, v237
	v_add_f32_e32 v244, v244, v245
	v_add_f32_e32 v130, v130, v131
	ds_bpermute_b32 v197, v252, v196
	ds_bpermute_b32 v205, v252, v204
	ds_bpermute_b32 v213, v252, v212
	ds_bpermute_b32 v221, v252, v220
	ds_bpermute_b32 v229, v252, v228
	ds_bpermute_b32 v237, v252, v236
	ds_bpermute_b32 v245, v252, v244
	ds_bpermute_b32 v131, v252, v130
	s_waitcnt lgkmcnt(0)
	v_add_f32_e32 v196, v196, v197
	v_add_f32_e32 v204, v204, v205
	v_add_f32_e32 v212, v212, v213
	v_add_f32_e32 v220, v220, v221
	v_add_f32_e32 v228, v228, v229
	v_add_f32_e32 v236, v236, v237
	v_add_f32_e32 v244, v244, v245
	v_add_f32_e32 v130, v130, v131
	s_lshl_b32 s4, s1, 6
	s_lshl_b32 s5, s10, 4
	s_add_u32 s4, s4, s5
	s_lshl_b32 s5, s53, 2
	s_add_u32 s4, s4, s5
	s_add_u32 s38, s16, s4
	s_addc_u32 s39, s17, 0
	s_add_u32 s36, s38, 0x2000
	s_addc_u32 s37, s39, 0
	s_mov_b64 exec, 0xffff
	global_store_dword v146, v196, s[38:39] offset:0 sc0 sc1
	global_store_dword v146, v204, s[38:39] offset:1024 sc0 sc1
	global_store_dword v146, v212, s[38:39] offset:2048 sc0 sc1
	global_store_dword v146, v220, s[38:39] offset:3072 sc0 sc1
	global_store_dword v146, v228, s[36:37] offset:0 sc0 sc1
	global_store_dword v146, v236, s[36:37] offset:1024 sc0 sc1
	global_store_dword v146, v244, s[36:37] offset:2048 sc0 sc1
	global_store_dword v146, v130, s[36:37] offset:3072 sc0 sc1
	s_mov_b64 exec, -1
	s_waitcnt vmcnt(0)
	s_barrier
	v_cmp_eq_u32_e32 vcc, 0, v0
	s_and_saveexec_b64 s[30:31], vcc
	s_cbranch_execz .Lf9_sync_done
	s_lshl_b32 s4, s98, 2
	s_add_u32 s4, s4, 0x83800
	s_add_u32 s4, s78, s4
	s_addc_u32 s5, s79, 0
	v_mov_b32_e32 v253, 0
	v_mov_b32_e32 v172, 1
	global_atomic_add v173, v253, v172, s[4:5] sc0
	s_mov_b32 s6, 0
	s_waitcnt vmcnt(0)
	v_readfirstlane_b32 s7, v173
	s_nop 3
	s_cmp_ge_u32 s7, 3
	s_cbranch_scc1 .Lf9_sync_done
